# K-loops: no setprio flips + per-phase counted vmcnt(10) (each LDS-DMA stage gets 5 phases to land)
# speedup vs baseline: 1.0018x; 1.0013x over previous
.LBB0_100:
	ds_read_b128 v[146:149], v143
	ds_read_b128 v[150:153], v143 offset:1024
	ds_read_b128 v[154:157], v143 offset:2048
	ds_read_b128 v[158:161], v143 offset:3072
	s_add_u32 s20, s18, 0xfffc0080
	s_addc_u32 s21, s19, -1
	s_cmp_eq_u32 s62, 12
	s_cselect_b32 s23, s11, s21
	s_cselect_b32 s22, s50, s20
	s_cselect_b32 s21, s13, s61
	s_cselect_b32 s20, s51, s60
	v_lshl_add_u64 v[194:195], s[18:19], 0, v[132:133]
	s_add_i32 m0, s9, 0xc000
	ds_read_b128 v[162:165], v144
	ds_read_b128 v[166:169], v144 offset:1024
	ds_read_b128 v[170:173], v144 offset:2048
	ds_read_b128 v[174:177], v144 offset:3072
	ds_read_b128 v[178:181], v144 offset:4096
	ds_read_b128 v[182:185], v144 offset:5120
	ds_read_b128 v[186:189], v144 offset:6144
	ds_read_b128 v[190:193], v144 offset:7168
	global_load_lds_dwordx4 v[194:195], off
	v_lshl_add_u64 v[194:195], s[18:19], 0, v[134:135]
	s_add_i32 m0, s9, 0xe000
	s_nop 0
	global_load_lds_dwordx4 v[194:195], off
	s_waitcnt lgkmcnt(8)
	s_waitcnt vmcnt(10)
	s_barrier
	s_waitcnt lgkmcnt(0)
	s_waitcnt lgkmcnt(0)
	v_mfma_f32_16x16x32_bf16 v[124:127], v[146:149], v[162:165], v[124:127]
	v_mfma_f32_16x16x32_bf16 v[120:123], v[154:157], v[162:165], v[120:123]
	v_mfma_f32_16x16x32_bf16 v[116:119], v[146:149], v[170:173], v[116:119]
	v_mfma_f32_16x16x32_bf16 v[108:111], v[154:157], v[170:173], v[108:111]
	v_mfma_f32_16x16x32_bf16 v[100:103], v[146:149], v[178:181], v[100:103]
	v_mfma_f32_16x16x32_bf16 v[92:95], v[154:157], v[178:181], v[92:95]
	v_mfma_f32_16x16x32_bf16 v[84:87], v[146:149], v[186:189], v[84:87]
	v_mfma_f32_16x16x32_bf16 v[76:79], v[154:157], v[186:189], v[76:79]
	v_mfma_f32_16x16x32_bf16 v[124:127], v[150:153], v[166:169], v[124:127]
	v_mfma_f32_16x16x32_bf16 v[120:123], v[158:161], v[166:169], v[120:123]
	v_mfma_f32_16x16x32_bf16 v[116:119], v[150:153], v[174:177], v[116:119]
	v_mfma_f32_16x16x32_bf16 v[108:111], v[158:161], v[174:177], v[108:111]
	v_mfma_f32_16x16x32_bf16 v[100:103], v[150:153], v[182:185], v[100:103]
	v_mfma_f32_16x16x32_bf16 v[92:95], v[158:161], v[182:185], v[92:95]
	v_mfma_f32_16x16x32_bf16 v[84:87], v[150:153], v[190:193], v[84:87]
	v_mfma_f32_16x16x32_bf16 v[76:79], v[158:161], v[190:193], v[76:79]
	s_barrier
	s_add_i32 s63, s47, s35
	v_lshl_add_u64 v[210:211], s[20:21], 0, v[128:129]
	s_mov_b32 m0, s63
	ds_read_b128 v[194:197], v145
	ds_read_b128 v[198:201], v145 offset:1024
	ds_read_b128 v[202:205], v145 offset:2048
	ds_read_b128 v[206:209], v145 offset:3072
	global_load_lds_dwordx4 v[210:211], off
	v_lshl_add_u64 v[212:213], s[20:21], 0, v[130:131]
	s_add_i32 m0, s63, 0x2000
	s_nop 0
	global_load_lds_dwordx4 v[212:213], off
	s_waitcnt vmcnt(10)
	s_barrier
	s_waitcnt lgkmcnt(0)
	s_waitcnt lgkmcnt(0)
	v_mfma_f32_16x16x32_bf16 v[112:115], v[194:197], v[162:165], v[112:115]
	v_mfma_f32_16x16x32_bf16 v[104:107], v[202:205], v[162:165], v[104:107]
	v_mfma_f32_16x16x32_bf16 v[96:99], v[194:197], v[170:173], v[96:99]
	v_mfma_f32_16x16x32_bf16 v[88:91], v[202:205], v[170:173], v[88:91]
	v_mfma_f32_16x16x32_bf16 v[80:83], v[194:197], v[178:181], v[80:83]
	v_mfma_f32_16x16x32_bf16 v[72:75], v[202:205], v[178:181], v[72:75]
	v_mfma_f32_16x16x32_bf16 v[68:71], v[194:197], v[186:189], v[68:71]
	v_mfma_f32_16x16x32_bf16 v[64:67], v[202:205], v[186:189], v[64:67]
	v_mfma_f32_16x16x32_bf16 v[112:115], v[198:201], v[166:169], v[112:115]
	v_mfma_f32_16x16x32_bf16 v[104:107], v[206:209], v[166:169], v[104:107]
	v_mfma_f32_16x16x32_bf16 v[96:99], v[198:201], v[174:177], v[96:99]
	v_mfma_f32_16x16x32_bf16 v[88:91], v[206:209], v[174:177], v[88:91]
	v_mfma_f32_16x16x32_bf16 v[80:83], v[198:201], v[182:185], v[80:83]
	v_mfma_f32_16x16x32_bf16 v[72:75], v[206:209], v[182:185], v[72:75]
	v_mfma_f32_16x16x32_bf16 v[68:71], v[198:201], v[190:193], v[68:71]
	v_mfma_f32_16x16x32_bf16 v[64:67], v[206:209], v[190:193], v[64:67]
	s_mov_b32 m0, s9
	v_lshl_add_u64 v[214:215], s[22:23], 0, v[128:129]
	s_barrier
	ds_read_b128 v[162:165], v144 offset:16384
	ds_read_b128 v[166:169], v144 offset:17408
	ds_read_b128 v[170:173], v144 offset:18432
	ds_read_b128 v[174:177], v144 offset:19456
	ds_read_b128 v[178:181], v144 offset:20480
	ds_read_b128 v[182:185], v144 offset:21504
	ds_read_b128 v[186:189], v144 offset:22528
	ds_read_b128 v[190:193], v144 offset:23552
	global_load_lds_dwordx4 v[214:215], off
	v_lshl_add_u64 v[216:217], s[22:23], 0, v[130:131]
	s_mov_b32 m0, s36
	s_nop 0
	global_load_lds_dwordx4 v[216:217], off
	s_barrier
	s_waitcnt lgkmcnt(0)
	s_waitcnt lgkmcnt(0)
	v_mfma_f32_16x16x32_bf16 v[60:63], v[146:149], v[162:165], v[60:63]
	v_mfma_f32_16x16x32_bf16 v[56:59], v[154:157], v[162:165], v[56:59]
	v_mfma_f32_16x16x32_bf16 v[52:55], v[146:149], v[170:173], v[52:55]
	v_mfma_f32_16x16x32_bf16 v[48:51], v[154:157], v[170:173], v[48:51]
	v_mfma_f32_16x16x32_bf16 v[36:39], v[146:149], v[178:181], v[36:39]
	v_mfma_f32_16x16x32_bf16 v[32:35], v[154:157], v[178:181], v[32:35]
	v_mfma_f32_16x16x32_bf16 v[20:23], v[146:149], v[186:189], v[20:23]
	v_mfma_f32_16x16x32_bf16 v[16:19], v[154:157], v[186:189], v[16:19]
	v_mfma_f32_16x16x32_bf16 v[60:63], v[150:153], v[166:169], v[60:63]
	v_mfma_f32_16x16x32_bf16 v[56:59], v[158:161], v[166:169], v[56:59]
	v_mfma_f32_16x16x32_bf16 v[52:55], v[150:153], v[174:177], v[52:55]
	v_mfma_f32_16x16x32_bf16 v[48:51], v[158:161], v[174:177], v[48:51]
	v_mfma_f32_16x16x32_bf16 v[36:39], v[150:153], v[182:185], v[36:39]
	v_mfma_f32_16x16x32_bf16 v[32:35], v[158:161], v[182:185], v[32:35]
	v_mfma_f32_16x16x32_bf16 v[20:23], v[150:153], v[190:193], v[20:23]
	v_mfma_f32_16x16x32_bf16 v[16:19], v[158:161], v[190:193], v[16:19]
	s_barrier
	s_add_u32 s68, s20, 0x40000
	s_addc_u32 s69, s21, 0
	s_add_i32 s63, s48, s35
	v_lshl_add_u64 v[146:147], s[68:69], 0, v[128:129]
	s_mov_b32 m0, s63
	s_nop 0
	global_load_lds_dwordx4 v[146:147], off
	v_lshl_add_u64 v[146:147], s[68:69], 0, v[130:131]
	s_add_i32 m0, s63, 0x2000
	s_nop 0
	global_load_lds_dwordx4 v[146:147], off
	s_waitcnt vmcnt(10)
	s_barrier
	v_mfma_f32_16x16x32_bf16 v[44:47], v[194:197], v[162:165], v[44:47]
	v_mfma_f32_16x16x32_bf16 v[40:43], v[202:205], v[162:165], v[40:43]
	v_mfma_f32_16x16x32_bf16 v[28:31], v[194:197], v[170:173], v[28:31]
	v_mfma_f32_16x16x32_bf16 v[24:27], v[202:205], v[170:173], v[24:27]
	v_mfma_f32_16x16x32_bf16 v[12:15], v[194:197], v[178:181], v[12:15]
	v_mfma_f32_16x16x32_bf16 v[8:11], v[202:205], v[178:181], v[8:11]
	v_mfma_f32_16x16x32_bf16 v[4:7], v[194:197], v[186:189], v[4:7]
	v_mfma_f32_16x16x32_bf16 v[0:3], v[202:205], v[186:189], v[0:3]
	v_mfma_f32_16x16x32_bf16 v[44:47], v[198:201], v[166:169], v[44:47]
	v_mfma_f32_16x16x32_bf16 v[40:43], v[206:209], v[166:169], v[40:43]
	v_mfma_f32_16x16x32_bf16 v[28:31], v[198:201], v[174:177], v[28:31]
	v_mfma_f32_16x16x32_bf16 v[24:27], v[206:209], v[174:177], v[24:27]
	v_mfma_f32_16x16x32_bf16 v[12:15], v[198:201], v[182:185], v[12:15]
	v_mfma_f32_16x16x32_bf16 v[8:11], v[206:209], v[182:185], v[8:11]
	v_mfma_f32_16x16x32_bf16 v[4:7], v[198:201], v[190:193], v[4:7]
	v_mfma_f32_16x16x32_bf16 v[0:3], v[206:209], v[190:193], v[0:3]
	s_add_i32 s63, 0, 0x18000
	v_add_u32_e32 v158, s63, v141
	s_barrier
	ds_read_b128 v[146:149], v158
	ds_read_b128 v[150:153], v158 offset:1024
	ds_read_b128 v[154:157], v158 offset:2048
	ds_read_b128 v[158:161], v158 offset:3072
	s_add_u32 s22, s22, 0x40000
	s_addc_u32 s23, s23, 0
	s_mov_b32 m0, s37
	v_lshl_add_u64 v[194:195], s[22:23], 0, v[128:129]
	ds_read_b128 v[162:165], v144 offset:32768
	ds_read_b128 v[166:169], v144 offset:33792
	ds_read_b128 v[170:173], v144 offset:34816
	ds_read_b128 v[174:177], v144 offset:35840
	ds_read_b128 v[178:181], v144 offset:36864
	ds_read_b128 v[182:185], v144 offset:37888
	ds_read_b128 v[186:189], v144 offset:38912
	ds_read_b128 v[190:193], v144 offset:39936
	global_load_lds_dwordx4 v[194:195], off
	v_lshl_add_u64 v[194:195], s[22:23], 0, v[130:131]
	s_mov_b32 m0, s38
	s_nop 0
	global_load_lds_dwordx4 v[194:195], off
	s_waitcnt lgkmcnt(8)
	s_waitcnt vmcnt(10)
	s_barrier
	s_waitcnt lgkmcnt(0)
	s_waitcnt lgkmcnt(0)
	v_mfma_f32_16x16x32_bf16 v[124:127], v[146:149], v[162:165], v[124:127]
	v_mfma_f32_16x16x32_bf16 v[120:123], v[154:157], v[162:165], v[120:123]
	v_mfma_f32_16x16x32_bf16 v[116:119], v[146:149], v[170:173], v[116:119]
	v_mfma_f32_16x16x32_bf16 v[108:111], v[154:157], v[170:173], v[108:111]
	v_mfma_f32_16x16x32_bf16 v[100:103], v[146:149], v[178:181], v[100:103]
	v_mfma_f32_16x16x32_bf16 v[92:95], v[154:157], v[178:181], v[92:95]
	v_mfma_f32_16x16x32_bf16 v[84:87], v[146:149], v[186:189], v[84:87]
	v_mfma_f32_16x16x32_bf16 v[76:79], v[154:157], v[186:189], v[76:79]
	v_mfma_f32_16x16x32_bf16 v[124:127], v[150:153], v[166:169], v[124:127]
	v_mfma_f32_16x16x32_bf16 v[120:123], v[158:161], v[166:169], v[120:123]
	v_mfma_f32_16x16x32_bf16 v[116:119], v[150:153], v[174:177], v[116:119]
	v_mfma_f32_16x16x32_bf16 v[108:111], v[158:161], v[174:177], v[108:111]
	v_mfma_f32_16x16x32_bf16 v[100:103], v[150:153], v[182:185], v[100:103]
	v_mfma_f32_16x16x32_bf16 v[92:95], v[158:161], v[182:185], v[92:95]
	v_mfma_f32_16x16x32_bf16 v[84:87], v[150:153], v[190:193], v[84:87]
	v_mfma_f32_16x16x32_bf16 v[76:79], v[158:161], v[190:193], v[76:79]
	s_barrier
	s_add_i32 s22, 0, 0x1c000
	s_add_i32 s23, s63, s35
	v_add_u32_e32 v206, s22, v141
	v_lshl_add_u64 v[210:211], v[210:211], 0, s[6:7]
	s_mov_b32 m0, s23
	ds_read_b128 v[194:197], v206
	ds_read_b128 v[198:201], v206 offset:1024
	ds_read_b128 v[202:205], v206 offset:2048
	ds_read_b128 v[206:209], v206 offset:3072
	global_load_lds_dwordx4 v[210:211], off
	v_lshl_add_u64 v[210:211], v[212:213], 0, s[6:7]
	s_add_i32 m0, s23, 0x2000
	s_nop 0
	global_load_lds_dwordx4 v[210:211], off
	s_waitcnt vmcnt(10)
	s_barrier
	s_waitcnt lgkmcnt(0)
	s_waitcnt lgkmcnt(0)
	v_mfma_f32_16x16x32_bf16 v[112:115], v[194:197], v[162:165], v[112:115]
	v_mfma_f32_16x16x32_bf16 v[104:107], v[202:205], v[162:165], v[104:107]
	v_mfma_f32_16x16x32_bf16 v[96:99], v[194:197], v[170:173], v[96:99]
	v_mfma_f32_16x16x32_bf16 v[88:91], v[202:205], v[170:173], v[88:91]
	v_mfma_f32_16x16x32_bf16 v[80:83], v[194:197], v[178:181], v[80:83]
	v_mfma_f32_16x16x32_bf16 v[72:75], v[202:205], v[178:181], v[72:75]
	v_mfma_f32_16x16x32_bf16 v[68:71], v[194:197], v[186:189], v[68:71]
	v_mfma_f32_16x16x32_bf16 v[64:67], v[202:205], v[186:189], v[64:67]
	v_mfma_f32_16x16x32_bf16 v[112:115], v[198:201], v[166:169], v[112:115]
	v_mfma_f32_16x16x32_bf16 v[104:107], v[206:209], v[166:169], v[104:107]
	v_mfma_f32_16x16x32_bf16 v[96:99], v[198:201], v[174:177], v[96:99]
	v_mfma_f32_16x16x32_bf16 v[88:91], v[206:209], v[174:177], v[88:91]
	v_mfma_f32_16x16x32_bf16 v[80:83], v[198:201], v[182:185], v[80:83]
	v_mfma_f32_16x16x32_bf16 v[72:75], v[206:209], v[182:185], v[72:75]
	v_mfma_f32_16x16x32_bf16 v[68:71], v[198:201], v[190:193], v[68:71]
	v_mfma_f32_16x16x32_bf16 v[64:67], v[206:209], v[190:193], v[64:67]
	s_mov_b32 m0, s41
	v_lshl_add_u64 v[210:211], v[214:215], 0, s[6:7]
	s_barrier
	ds_read_b128 v[162:165], v144 offset:49152
	ds_read_b128 v[166:169], v144 offset:50176
	ds_read_b128 v[170:173], v144 offset:51200
	ds_read_b128 v[174:177], v144 offset:52224
	ds_read_b128 v[178:181], v144 offset:53248
	ds_read_b128 v[182:185], v144 offset:54272
	ds_read_b128 v[186:189], v144 offset:55296
	ds_read_b128 v[190:193], v144 offset:56320
	global_load_lds_dwordx4 v[210:211], off
	v_lshl_add_u64 v[210:211], v[216:217], 0, s[6:7]
	s_mov_b32 m0, s43
	s_nop 0
	global_load_lds_dwordx4 v[210:211], off
	s_barrier
	s_waitcnt lgkmcnt(0)
	s_waitcnt lgkmcnt(0)
	v_mfma_f32_16x16x32_bf16 v[60:63], v[146:149], v[162:165], v[60:63]
	v_mfma_f32_16x16x32_bf16 v[56:59], v[154:157], v[162:165], v[56:59]
	v_mfma_f32_16x16x32_bf16 v[52:55], v[146:149], v[170:173], v[52:55]
	v_mfma_f32_16x16x32_bf16 v[48:51], v[154:157], v[170:173], v[48:51]
	v_mfma_f32_16x16x32_bf16 v[36:39], v[146:149], v[178:181], v[36:39]
	v_mfma_f32_16x16x32_bf16 v[32:35], v[154:157], v[178:181], v[32:35]
	v_mfma_f32_16x16x32_bf16 v[20:23], v[146:149], v[186:189], v[20:23]
	v_mfma_f32_16x16x32_bf16 v[16:19], v[154:157], v[186:189], v[16:19]
	v_mfma_f32_16x16x32_bf16 v[60:63], v[150:153], v[166:169], v[60:63]
	v_mfma_f32_16x16x32_bf16 v[56:59], v[158:161], v[166:169], v[56:59]
	v_mfma_f32_16x16x32_bf16 v[52:55], v[150:153], v[174:177], v[52:55]
	v_mfma_f32_16x16x32_bf16 v[48:51], v[158:161], v[174:177], v[48:51]
	v_mfma_f32_16x16x32_bf16 v[36:39], v[150:153], v[182:185], v[36:39]
	v_mfma_f32_16x16x32_bf16 v[32:35], v[158:161], v[182:185], v[32:35]
	v_mfma_f32_16x16x32_bf16 v[20:23], v[150:153], v[190:193], v[20:23]
	v_mfma_f32_16x16x32_bf16 v[16:19], v[158:161], v[190:193], v[16:19]
	s_barrier
	s_add_u32 s20, s20, 0x40080
	s_addc_u32 s21, s21, 0
	s_add_i32 s22, s22, s35
	v_lshl_add_u64 v[146:147], s[20:21], 0, v[128:129]
	s_mov_b32 m0, s22
	s_nop 0
	global_load_lds_dwordx4 v[146:147], off
	v_lshl_add_u64 v[146:147], s[20:21], 0, v[130:131]
	s_add_i32 m0, s22, 0x2000
	s_nop 0
	global_load_lds_dwordx4 v[146:147], off
	s_waitcnt vmcnt(10)
	s_barrier
	v_mfma_f32_16x16x32_bf16 v[44:47], v[194:197], v[162:165], v[44:47]
	v_mfma_f32_16x16x32_bf16 v[40:43], v[202:205], v[162:165], v[40:43]
	v_mfma_f32_16x16x32_bf16 v[28:31], v[194:197], v[170:173], v[28:31]
	v_mfma_f32_16x16x32_bf16 v[24:27], v[202:205], v[170:173], v[24:27]
	v_mfma_f32_16x16x32_bf16 v[12:15], v[194:197], v[178:181], v[12:15]
	v_mfma_f32_16x16x32_bf16 v[8:11], v[202:205], v[178:181], v[8:11]
	v_mfma_f32_16x16x32_bf16 v[4:7], v[194:197], v[186:189], v[4:7]
	v_mfma_f32_16x16x32_bf16 v[0:3], v[202:205], v[186:189], v[0:3]
	v_mfma_f32_16x16x32_bf16 v[44:47], v[198:201], v[166:169], v[44:47]
	v_mfma_f32_16x16x32_bf16 v[40:43], v[206:209], v[166:169], v[40:43]
	v_mfma_f32_16x16x32_bf16 v[28:31], v[198:201], v[174:177], v[28:31]
	v_mfma_f32_16x16x32_bf16 v[24:27], v[206:209], v[174:177], v[24:27]
	v_mfma_f32_16x16x32_bf16 v[12:15], v[198:201], v[182:185], v[12:15]
	v_mfma_f32_16x16x32_bf16 v[8:11], v[206:209], v[182:185], v[8:11]
	v_mfma_f32_16x16x32_bf16 v[4:7], v[198:201], v[190:193], v[4:7]
	v_mfma_f32_16x16x32_bf16 v[0:3], v[206:209], v[190:193], v[0:3]
	s_add_i32 s62, s62, 2
	s_add_u32 s18, s18, 0x100
	s_addc_u32 s19, s19, 0
	s_add_u32 s60, s60, 0x100
	s_addc_u32 s61, s61, 0
	s_cmp_gt_u32 s62, 13
	s_barrier
	s_cbranch_scc0 .LBB0_100
	v_lshl_add_u32 v148, s8, 8, v140
	v_lshl_or_b32 v146, s49, 8, v142
	v_ashrrev_i32_e32 v149, 31, v148
	v_cvt_pk_bf16_f32 v112, v112, v113
	v_cvt_pk_bf16_f32 v113, v114, v115
	v_cvt_pk_bf16_f32 v114, v104, v105
	v_or_b32_e32 v104, 16, v148
	v_ashrrev_i32_e32 v147, 31, v146
	v_lshlrev_b64 v[150:151], 11, v[148:149]
	v_ashrrev_i32_e32 v105, 31, v104
	v_cvt_pk_bf16_f32 v96, v96, v97
	v_cvt_pk_bf16_f32 v97, v98, v99
	v_cvt_pk_bf16_f32 v98, v88, v89
	v_or_b32_e32 v88, 32, v148
	v_lshl_add_u64 v[150:151], s[2:3], 0, v[150:151]
	v_lshlrev_b64 v[146:147], 1, v[146:147]
	v_lshlrev_b64 v[104:105], 11, v[104:105]
	v_ashrrev_i32_e32 v89, 31, v88
	v_cvt_pk_bf16_f32 v80, v80, v81
	v_cvt_pk_bf16_f32 v81, v82, v83
	v_cvt_pk_bf16_f32 v82, v72, v73
	v_or_b32_e32 v72, 48, v148
	v_cvt_pk_bf16_f32 v68, v68, v69
	v_cvt_pk_bf16_f32 v69, v70, v71
	v_cvt_pk_bf16_f32 v70, v64, v65
	v_add_u32_e32 v64, 0x80, v148
	v_lshl_add_u64 v[150:151], v[150:151], 0, v[146:147]
	v_cvt_pk_bf16_f32 v124, v124, v125
	v_cvt_pk_bf16_f32 v125, v126, v127
	v_cvt_pk_bf16_f32 v126, v120, v121
	v_cvt_pk_bf16_f32 v127, v122, v123
	v_lshl_add_u64 v[104:105], s[2:3], 0, v[104:105]
	v_lshlrev_b64 v[88:89], 11, v[88:89]
	v_ashrrev_i32_e32 v73, 31, v72
	v_ashrrev_i32_e32 v65, 31, v64
	v_cvt_pk_bf16_f32 v44, v44, v45
	v_cvt_pk_bf16_f32 v45, v46, v47
	v_cvt_pk_bf16_f32 v46, v40, v41
	v_add_u32_e32 v40, 0x90, v148
	v_cvt_pk_bf16_f32 v115, v106, v107
	global_store_dwordx4 v[150:151], v[124:127], off
	global_store_dwordx4 v[150:151], v[112:115], off offset:64
	v_cvt_pk_bf16_f32 v106, v108, v109
	v_cvt_pk_bf16_f32 v107, v110, v111
	v_lshl_add_u64 v[112:113], v[104:105], 0, v[146:147]
	v_cvt_pk_bf16_f32 v104, v116, v117
	v_cvt_pk_bf16_f32 v105, v118, v119
	v_lshl_add_u64 v[88:89], s[2:3], 0, v[88:89]
	v_lshlrev_b64 v[72:73], 11, v[72:73]
	v_lshlrev_b64 v[64:65], 11, v[64:65]
	v_ashrrev_i32_e32 v41, 31, v40
	v_cvt_pk_bf16_f32 v28, v28, v29
	v_cvt_pk_bf16_f32 v29, v30, v31
	v_cvt_pk_bf16_f32 v30, v24, v25
	v_add_u32_e32 v24, 0xa0, v148
	v_cvt_pk_bf16_f32 v99, v90, v91
	global_store_dwordx4 v[112:113], v[104:107], off
	global_store_dwordx4 v[112:113], v[96:99], off offset:64
	v_cvt_pk_bf16_f32 v90, v92, v93
	v_cvt_pk_bf16_f32 v91, v94, v95
	v_lshl_add_u64 v[96:97], v[88:89], 0, v[146:147]
	v_cvt_pk_bf16_f32 v88, v100, v101
	v_cvt_pk_bf16_f32 v89, v102, v103
	v_lshl_add_u64 v[72:73], s[2:3], 0, v[72:73]
	v_lshl_add_u64 v[64:65], s[2:3], 0, v[64:65]
	v_lshlrev_b64 v[40:41], 11, v[40:41]
	v_ashrrev_i32_e32 v25, 31, v24
	v_cvt_pk_bf16_f32 v12, v12, v13
	v_cvt_pk_bf16_f32 v13, v14, v15
	v_cvt_pk_bf16_f32 v14, v8, v9
	v_add_u32_e32 v8, 0xb0, v148
	v_cvt_pk_bf16_f32 v83, v74, v75
	global_store_dwordx4 v[96:97], v[88:91], off
	global_store_dwordx4 v[96:97], v[80:83], off offset:64
	v_cvt_pk_bf16_f32 v74, v76, v77
	v_cvt_pk_bf16_f32 v75, v78, v79
	v_lshl_add_u64 v[80:81], v[72:73], 0, v[146:147]
	v_cvt_pk_bf16_f32 v72, v84, v85
	v_cvt_pk_bf16_f32 v73, v86, v87
	v_lshl_add_u64 v[64:65], v[64:65], 0, v[146:147]
	v_cvt_pk_bf16_f32 v60, v60, v61
	v_cvt_pk_bf16_f32 v61, v62, v63
	v_cvt_pk_bf16_f32 v62, v56, v57
	v_cvt_pk_bf16_f32 v63, v58, v59
	v_lshl_add_u64 v[40:41], s[2:3], 0, v[40:41]
	v_lshlrev_b64 v[24:25], 11, v[24:25]
	v_ashrrev_i32_e32 v9, 31, v8
	v_cvt_pk_bf16_f32 v71, v66, v67
	global_store_dwordx4 v[80:81], v[72:75], off
	global_store_dwordx4 v[80:81], v[68:71], off offset:64
	v_cvt_pk_bf16_f32 v47, v42, v43
	global_store_dwordx4 v[64:65], v[60:63], off
	global_store_dwordx4 v[64:65], v[44:47], off offset:64
	v_cvt_pk_bf16_f32 v42, v48, v49
	v_cvt_pk_bf16_f32 v43, v50, v51
	v_lshl_add_u64 v[44:45], v[40:41], 0, v[146:147]
	v_cvt_pk_bf16_f32 v40, v52, v53
	v_cvt_pk_bf16_f32 v41, v54, v55
	v_lshl_add_u64 v[24:25], s[2:3], 0, v[24:25]
	v_lshlrev_b64 v[8:9], 11, v[8:9]
	v_cvt_pk_bf16_f32 v31, v26, v27
	global_store_dwordx4 v[44:45], v[40:43], off
	global_store_dwordx4 v[44:45], v[28:31], off offset:64
	v_cvt_pk_bf16_f32 v26, v32, v33
	v_cvt_pk_bf16_f32 v27, v34, v35
	v_lshl_add_u64 v[28:29], v[24:25], 0, v[146:147]
	v_cvt_pk_bf16_f32 v24, v36, v37
	v_cvt_pk_bf16_f32 v25, v38, v39
	v_lshl_add_u64 v[8:9], s[2:3], 0, v[8:9]
	v_cvt_pk_bf16_f32 v15, v10, v11
	global_store_dwordx4 v[28:29], v[24:27], off
	global_store_dwordx4 v[28:29], v[12:15], off offset:64
	v_cvt_pk_bf16_f32 v10, v16, v17
	v_cvt_pk_bf16_f32 v11, v18, v19
	v_lshl_add_u64 v[12:13], v[8:9], 0, v[146:147]
	v_cvt_pk_bf16_f32 v8, v20, v21
	v_cvt_pk_bf16_f32 v9, v22, v23
	s_and_b64 vcc, exec, s[4:5]
	s_mov_b32 s49, s12
	s_mov_b32 s8, s10
	s_mov_b64 s[20:21], s[16:17]
	s_mov_b64 s[18:19], s[14:15]
	v_cvt_pk_bf16_f32 v4, v4, v5
	v_cvt_pk_bf16_f32 v5, v6, v7
	v_cvt_pk_bf16_f32 v6, v0, v1
	v_cvt_pk_bf16_f32 v7, v2, v3
	global_store_dwordx4 v[12:13], v[8:11], off
	global_store_dwordx4 v[12:13], v[4:7], off offset:64
	s_cbranch_vccz .LBB0_93
	s_waitcnt vmcnt(0)
	s_cmpk_gt_u32 s27, 0xff
	s_cbranch_scc1 .LBB0_104
	s_barrier

.LBB0_174:
	v_lshrrev_b32_e32 v18, 1, v15
	s_add_u32 s46, s9, 0x19c00000
	v_and_b32_e32 v18, 24, v18
	s_addc_u32 s47, s10, 0
	v_and_b32_e32 v16, 15, v15
	s_lshl_b32 s17, s1, 6
	v_lshlrev_b32_e32 v19, 1, v18
	v_lshlrev_b32_e32 v15, 2, v15
	s_and_b32 s6, s0, 3
	v_or_b32_e32 v17, s17, v16
	v_lshl_or_b32 v16, v16, 6, v19
	s_lshl_b32 s0, s1, 13
	v_and_b32_e32 v15, 32, v15
	s_add_i32 m0, s73, 0x18000
	v_lshl_add_u64 v[8:9], v[8:9], 0, s[24:25]
	v_bitop3_b32 v19, v16, s0, v15 bitop3:0xde
	s_lshl_b32 s0, s6, 12
	s_waitcnt vmcnt(4)
	s_barrier
	global_load_lds_dwordx4 v[8:9], off
	v_lshl_add_u64 v[6:7], v[6:7], 0, s[24:25]
	s_add_i32 m0, s73, 0x1a000
	s_add_i32 s18, s73, 0x8000
	s_add_i32 s19, s73, 0xa000
	v_bitop3_b32 v155, v16, s0, v15 bitop3:0xde
	global_load_lds_dwordx4 v[6:7], off
	v_lshl_add_u64 v[4:5], v[4:5], 0, s[24:25]
	s_mov_b32 m0, s18
	s_add_u32 s0, s62, 0x40080
	global_load_lds_dwordx4 v[4:5], off
	v_lshl_add_u64 v[2:3], v[2:3], 0, s[24:25]
	s_mov_b32 m0, s19
	s_addc_u32 s1, s63, 0
	global_load_lds_dwordx4 v[2:3], off
	s_add_i32 m0, s73, 0x1c000
	v_lshl_add_u64 v[2:3], s[0:1], 0, v[146:147]
	global_load_lds_dwordx4 v[2:3], off
	v_lshl_add_u64 v[2:3], s[0:1], 0, v[148:149]
	s_add_i32 m0, s73, 0x1e000
	v_add_u32_e32 v245, 0x80, v17
	global_load_lds_dwordx4 v[2:3], off
	v_lshlrev_b32_e32 v2, 8, v17
	v_and_b32_e32 v244, 0xcf00, v2
	v_lshlrev_b32_e32 v2, 8, v245
	v_add_u32_e32 v247, 0x90, v17
	v_and_b32_e32 v246, 0xcf00, v2
	v_lshlrev_b32_e32 v2, 8, v247
	v_add_u32_e32 v249, 0xa0, v17
	v_and_b32_e32 v248, 0xdf00, v2
	v_lshlrev_b32_e32 v2, 8, v249
	v_add_u32_e32 v251, 0xb0, v17
	v_and_b32_e32 v250, 0xef00, v2
	v_lshlrev_b32_e32 v2, 8, v251
	v_and_b32_e32 v252, 0xff00, v2
	v_lshlrev_b32_e32 v2, 14, v0
	v_and_b32_e32 v2, 0xffff8000, v2
	v_lshl_add_u32 v2, v10, 11, v2
	v_and_b32_e32 v0, 1, v0
	v_lshl_or_b32 v0, v0, 6, v2
	v_lshl_add_u32 v150, v11, 1, v0
	v_lshlrev_b32_e32 v0, 14, v12
	v_and_b32_e32 v0, 0xffff8000, v0
	s_waitcnt vmcnt(6)
	v_lshl_add_u32 v0, v13, 11, v0
	v_and_b32_e32 v2, 1, v12
	s_add_i32 s0, 0, 0x20000
	v_lshl_or_b32 v0, v2, 6, v0
	v_lshl_add_u32 v179, v18, 2, s0
	s_ashr_i32 s20, s48, 31
	v_lshl_or_b32 v253, s6, 6, v18
	v_mov_b32_e32 v151, v1
	v_lshl_add_u32 v152, v14, 1, v0
	v_mov_b32_e32 v153, v1
	s_mov_b32 s21, 0
	v_add_u32_e32 v231, 0, v19
	s_barrier
	s_branch .LBB0_176
	s_nop 0
	s_nop 0
	s_nop 0
	s_nop 0
	s_nop 0
	s_nop 0
	s_nop 0
	s_nop 0
	s_nop 0
	s_nop 0
	s_nop 0
	s_nop 0

.LBB0_179:
	s_add_u32 s6, s2, 0xfffc0080
	s_addc_u32 s7, s3, -1
	s_add_i32 s33, 0, 0x10000
	v_add_u32_e32 v0, s33, v155
	ds_read_b128 v[130:133], v0
	ds_read_b128 v[134:137], v0 offset:1024
	ds_read_b128 v[138:141], v0 offset:2048
	ds_read_b128 v[142:145], v0 offset:3072
	s_cmp_eq_u32 vcc_hi, 12
	s_cselect_b32 s91, s1, s7
	s_cselect_b32 s90, s22, s6
	s_cselect_b32 s63, s23, vcc_lo
	s_cselect_b32 s62, s39, s69
	v_lshl_add_u64 v[176:177], s[2:3], 0, v[150:151]
	s_add_i32 m0, s73, 0xc000
	ds_read_b128 v[156:159], v231
	ds_read_b128 v[160:163], v231 offset:1024
	ds_read_b128 v[164:167], v231 offset:2048
	ds_read_b128 v[168:171], v231 offset:3072
	ds_read_b128 v[172:175], v231 offset:4096
	ds_read_b128 v[184:187], v231 offset:5120
	ds_read_b128 v[188:191], v231 offset:6144
	ds_read_b128 v[192:195], v231 offset:7168
	global_load_lds_dwordx4 v[176:177], off
	v_lshl_add_u64 v[176:177], s[2:3], 0, v[152:153]
	s_add_i32 m0, s73, 0xe000
	s_nop 0
	global_load_lds_dwordx4 v[176:177], off
	s_waitcnt lgkmcnt(8)
	s_waitcnt vmcnt(10)
	s_barrier
	s_waitcnt lgkmcnt(0)
	s_waitcnt lgkmcnt(0)
	v_mfma_f32_16x16x32_bf16 v[126:129], v[130:133], v[156:159], v[126:129]
	v_mfma_f32_16x16x32_bf16 v[122:125], v[138:141], v[156:159], v[122:125]
	v_mfma_f32_16x16x32_bf16 v[110:113], v[130:133], v[164:167], v[110:113]
	v_mfma_f32_16x16x32_bf16 v[106:109], v[138:141], v[164:167], v[106:109]
	v_mfma_f32_16x16x32_bf16 v[94:97], v[130:133], v[172:175], v[94:97]
	v_mfma_f32_16x16x32_bf16 v[90:93], v[138:141], v[172:175], v[90:93]
	v_mfma_f32_16x16x32_bf16 v[78:81], v[130:133], v[188:191], v[78:81]
	v_mfma_f32_16x16x32_bf16 v[74:77], v[138:141], v[188:191], v[74:77]
	v_mfma_f32_16x16x32_bf16 v[126:129], v[134:137], v[160:163], v[126:129]
	v_mfma_f32_16x16x32_bf16 v[122:125], v[142:145], v[160:163], v[122:125]
	v_mfma_f32_16x16x32_bf16 v[110:113], v[134:137], v[168:171], v[110:113]
	v_mfma_f32_16x16x32_bf16 v[106:109], v[142:145], v[168:171], v[106:109]
	v_mfma_f32_16x16x32_bf16 v[94:97], v[134:137], v[184:187], v[94:97]
	v_mfma_f32_16x16x32_bf16 v[90:93], v[142:145], v[184:187], v[90:93]
	v_mfma_f32_16x16x32_bf16 v[78:81], v[134:137], v[192:195], v[78:81]
	v_mfma_f32_16x16x32_bf16 v[74:77], v[142:145], v[192:195], v[74:77]
	s_barrier
	s_add_i32 s94, 0, 0x14000
	s_add_i32 s6, s33, s11
	v_add_u32_e32 v0, s94, v155
	v_lshl_add_u64 v[176:177], s[62:63], 0, v[146:147]
	s_mov_b32 m0, s6
	ds_read_b128 v[196:199], v0
	ds_read_b128 v[200:203], v0 offset:1024
	ds_read_b128 v[204:207], v0 offset:2048
	ds_read_b128 v[208:211], v0 offset:3072
	global_load_lds_dwordx4 v[176:177], off
	v_lshl_add_u64 v[180:181], s[62:63], 0, v[148:149]
	s_add_i32 m0, s6, 0x2000
	s_nop 0
	global_load_lds_dwordx4 v[180:181], off
	s_waitcnt vmcnt(10)
	s_barrier
	s_waitcnt lgkmcnt(0)
	s_waitcnt lgkmcnt(0)
	v_mfma_f32_16x16x32_bf16 v[118:121], v[196:199], v[156:159], v[118:121]
	v_mfma_f32_16x16x32_bf16 v[114:117], v[204:207], v[156:159], v[114:117]
	v_mfma_f32_16x16x32_bf16 v[102:105], v[196:199], v[164:167], v[102:105]
	v_mfma_f32_16x16x32_bf16 v[98:101], v[204:207], v[164:167], v[98:101]
	v_mfma_f32_16x16x32_bf16 v[86:89], v[196:199], v[172:175], v[86:89]
	v_mfma_f32_16x16x32_bf16 v[82:85], v[204:207], v[172:175], v[82:85]
	v_mfma_f32_16x16x32_bf16 v[70:73], v[196:199], v[188:191], v[70:73]
	v_mfma_f32_16x16x32_bf16 v[66:69], v[204:207], v[188:191], v[66:69]
	v_mfma_f32_16x16x32_bf16 v[118:121], v[200:203], v[160:163], v[118:121]
	v_mfma_f32_16x16x32_bf16 v[114:117], v[208:211], v[160:163], v[114:117]
	v_mfma_f32_16x16x32_bf16 v[102:105], v[200:203], v[168:171], v[102:105]
	v_mfma_f32_16x16x32_bf16 v[98:101], v[208:211], v[168:171], v[98:101]
	v_mfma_f32_16x16x32_bf16 v[86:89], v[200:203], v[184:187], v[86:89]
	v_mfma_f32_16x16x32_bf16 v[82:85], v[208:211], v[184:187], v[82:85]
	v_mfma_f32_16x16x32_bf16 v[70:73], v[200:203], v[192:195], v[70:73]
	v_mfma_f32_16x16x32_bf16 v[66:69], v[208:211], v[192:195], v[66:69]
	s_mov_b32 m0, s73
	v_lshl_add_u64 v[212:213], s[90:91], 0, v[146:147]
	s_barrier
	ds_read_b128 v[156:159], v231 offset:16384
	ds_read_b128 v[160:163], v231 offset:17408
	ds_read_b128 v[164:167], v231 offset:18432
	ds_read_b128 v[168:171], v231 offset:19456
	ds_read_b128 v[172:175], v231 offset:20480
	ds_read_b128 v[184:187], v231 offset:21504
	ds_read_b128 v[188:191], v231 offset:22528
	ds_read_b128 v[192:195], v231 offset:23552
	global_load_lds_dwordx4 v[212:213], off
	v_lshl_add_u64 v[214:215], s[90:91], 0, v[148:149]
	s_mov_b32 m0, s14
	s_nop 0
	global_load_lds_dwordx4 v[214:215], off
	s_barrier
	s_waitcnt lgkmcnt(0)
	s_waitcnt lgkmcnt(0)
	v_mfma_f32_16x16x32_bf16 v[62:65], v[130:133], v[156:159], v[62:65]
	v_mfma_f32_16x16x32_bf16 v[58:61], v[138:141], v[156:159], v[58:61]
	v_mfma_f32_16x16x32_bf16 v[46:49], v[130:133], v[164:167], v[46:49]
	v_mfma_f32_16x16x32_bf16 v[42:45], v[138:141], v[164:167], v[42:45]
	v_mfma_f32_16x16x32_bf16 v[30:33], v[130:133], v[172:175], v[30:33]
	v_mfma_f32_16x16x32_bf16 v[26:29], v[138:141], v[172:175], v[26:29]
	v_mfma_f32_16x16x32_bf16 v[14:17], v[130:133], v[188:191], v[14:17]
	v_mfma_f32_16x16x32_bf16 v[10:13], v[138:141], v[188:191], v[10:13]
	v_mfma_f32_16x16x32_bf16 v[62:65], v[134:137], v[160:163], v[62:65]
	v_mfma_f32_16x16x32_bf16 v[58:61], v[142:145], v[160:163], v[58:61]
	v_mfma_f32_16x16x32_bf16 v[46:49], v[134:137], v[168:171], v[46:49]
	v_mfma_f32_16x16x32_bf16 v[42:45], v[142:145], v[168:171], v[42:45]
	v_mfma_f32_16x16x32_bf16 v[30:33], v[134:137], v[184:187], v[30:33]
	v_mfma_f32_16x16x32_bf16 v[26:29], v[142:145], v[184:187], v[26:29]
	v_mfma_f32_16x16x32_bf16 v[14:17], v[134:137], v[192:195], v[14:17]
	v_mfma_f32_16x16x32_bf16 v[10:13], v[142:145], v[192:195], v[10:13]
	s_barrier
	s_add_u32 s6, s62, 0x40000
	s_addc_u32 s7, s63, 0
	s_add_i32 s33, s94, s11
	v_lshl_add_u64 v[130:131], s[6:7], 0, v[146:147]
	s_mov_b32 m0, s33
	s_nop 0
	global_load_lds_dwordx4 v[130:131], off
	v_lshl_add_u64 v[130:131], s[6:7], 0, v[148:149]
	s_add_i32 m0, s33, 0x2000
	s_nop 0
	global_load_lds_dwordx4 v[130:131], off
	s_waitcnt vmcnt(10)
	s_barrier
	v_mfma_f32_16x16x32_bf16 v[54:57], v[196:199], v[156:159], v[54:57]
	v_mfma_f32_16x16x32_bf16 v[50:53], v[204:207], v[156:159], v[50:53]
	v_mfma_f32_16x16x32_bf16 v[38:41], v[196:199], v[164:167], v[38:41]
	v_mfma_f32_16x16x32_bf16 v[34:37], v[204:207], v[164:167], v[34:37]
	v_mfma_f32_16x16x32_bf16 v[22:25], v[196:199], v[172:175], v[22:25]
	v_mfma_f32_16x16x32_bf16 v[18:21], v[204:207], v[172:175], v[18:21]
	v_mfma_f32_16x16x32_bf16 v[6:9], v[196:199], v[188:191], v[6:9]
	v_mfma_f32_16x16x32_bf16 v[2:5], v[204:207], v[188:191], v[2:5]
	v_mfma_f32_16x16x32_bf16 v[54:57], v[200:203], v[160:163], v[54:57]
	v_mfma_f32_16x16x32_bf16 v[50:53], v[208:211], v[160:163], v[50:53]
	v_mfma_f32_16x16x32_bf16 v[38:41], v[200:203], v[168:171], v[38:41]
	v_mfma_f32_16x16x32_bf16 v[34:37], v[208:211], v[168:171], v[34:37]
	v_mfma_f32_16x16x32_bf16 v[22:25], v[200:203], v[184:187], v[22:25]
	v_mfma_f32_16x16x32_bf16 v[18:21], v[208:211], v[184:187], v[18:21]
	v_mfma_f32_16x16x32_bf16 v[6:9], v[200:203], v[192:195], v[6:9]
	v_mfma_f32_16x16x32_bf16 v[2:5], v[208:211], v[192:195], v[2:5]
	s_add_i32 s33, 0, 0x18000
	v_add_u32_e32 v0, s33, v155
	s_barrier
	ds_read_b128 v[130:133], v0
	ds_read_b128 v[134:137], v0 offset:1024
	ds_read_b128 v[138:141], v0 offset:2048
	ds_read_b128 v[142:145], v0 offset:3072
	s_add_u32 s6, s90, 0x40000
	s_addc_u32 s7, s91, 0
	s_mov_b32 m0, s15
	v_lshl_add_u64 v[196:197], s[6:7], 0, v[146:147]
	ds_read_b128 v[156:159], v231 offset:32768
	ds_read_b128 v[160:163], v231 offset:33792
	ds_read_b128 v[164:167], v231 offset:34816
	ds_read_b128 v[168:171], v231 offset:35840
	ds_read_b128 v[172:175], v231 offset:36864
	ds_read_b128 v[184:187], v231 offset:37888
	ds_read_b128 v[188:191], v231 offset:38912
	ds_read_b128 v[192:195], v231 offset:39936
	global_load_lds_dwordx4 v[196:197], off
	v_lshl_add_u64 v[196:197], s[6:7], 0, v[148:149]
	s_mov_b32 m0, s16
	s_nop 0
	global_load_lds_dwordx4 v[196:197], off
	s_waitcnt lgkmcnt(8)
	s_waitcnt vmcnt(10)
	s_barrier
	s_waitcnt lgkmcnt(0)
	s_waitcnt lgkmcnt(0)
	v_mfma_f32_16x16x32_bf16 v[126:129], v[130:133], v[156:159], v[126:129]
	v_mfma_f32_16x16x32_bf16 v[122:125], v[138:141], v[156:159], v[122:125]
	v_mfma_f32_16x16x32_bf16 v[110:113], v[130:133], v[164:167], v[110:113]
	v_mfma_f32_16x16x32_bf16 v[106:109], v[138:141], v[164:167], v[106:109]
	v_mfma_f32_16x16x32_bf16 v[94:97], v[130:133], v[172:175], v[94:97]
	v_mfma_f32_16x16x32_bf16 v[90:93], v[138:141], v[172:175], v[90:93]
	v_mfma_f32_16x16x32_bf16 v[78:81], v[130:133], v[188:191], v[78:81]
	v_mfma_f32_16x16x32_bf16 v[74:77], v[138:141], v[188:191], v[74:77]
	v_mfma_f32_16x16x32_bf16 v[126:129], v[134:137], v[160:163], v[126:129]
	v_mfma_f32_16x16x32_bf16 v[122:125], v[142:145], v[160:163], v[122:125]
	v_mfma_f32_16x16x32_bf16 v[110:113], v[134:137], v[168:171], v[110:113]
	v_mfma_f32_16x16x32_bf16 v[106:109], v[142:145], v[168:171], v[106:109]
	v_mfma_f32_16x16x32_bf16 v[94:97], v[134:137], v[184:187], v[94:97]
	v_mfma_f32_16x16x32_bf16 v[90:93], v[142:145], v[184:187], v[90:93]
	v_mfma_f32_16x16x32_bf16 v[78:81], v[134:137], v[192:195], v[78:81]
	v_mfma_f32_16x16x32_bf16 v[74:77], v[142:145], v[192:195], v[74:77]
	s_barrier
	s_add_i32 s90, 0, 0x1c000
	s_add_i32 s6, s33, s11
	v_add_u32_e32 v0, s90, v155
	v_lshl_add_u64 v[176:177], v[176:177], 0, s[24:25]
	s_mov_b32 m0, s6
	ds_read_b128 v[196:199], v0
	ds_read_b128 v[200:203], v0 offset:1024
	ds_read_b128 v[204:207], v0 offset:2048
	ds_read_b128 v[208:211], v0 offset:3072
	global_load_lds_dwordx4 v[176:177], off
	v_lshl_add_u64 v[176:177], v[180:181], 0, s[24:25]
	s_add_i32 m0, s6, 0x2000
	s_nop 0
	global_load_lds_dwordx4 v[176:177], off
	s_waitcnt vmcnt(10)
	s_barrier
	s_waitcnt lgkmcnt(0)
	s_waitcnt lgkmcnt(0)
	v_mfma_f32_16x16x32_bf16 v[118:121], v[196:199], v[156:159], v[118:121]
	v_mfma_f32_16x16x32_bf16 v[114:117], v[204:207], v[156:159], v[114:117]
	v_mfma_f32_16x16x32_bf16 v[102:105], v[196:199], v[164:167], v[102:105]
	v_mfma_f32_16x16x32_bf16 v[98:101], v[204:207], v[164:167], v[98:101]
	v_mfma_f32_16x16x32_bf16 v[86:89], v[196:199], v[172:175], v[86:89]
	v_mfma_f32_16x16x32_bf16 v[82:85], v[204:207], v[172:175], v[82:85]
	v_mfma_f32_16x16x32_bf16 v[70:73], v[196:199], v[188:191], v[70:73]
	v_mfma_f32_16x16x32_bf16 v[66:69], v[204:207], v[188:191], v[66:69]
	v_mfma_f32_16x16x32_bf16 v[118:121], v[200:203], v[160:163], v[118:121]
	v_mfma_f32_16x16x32_bf16 v[114:117], v[208:211], v[160:163], v[114:117]
	v_mfma_f32_16x16x32_bf16 v[102:105], v[200:203], v[168:171], v[102:105]
	v_mfma_f32_16x16x32_bf16 v[98:101], v[208:211], v[168:171], v[98:101]
	v_mfma_f32_16x16x32_bf16 v[86:89], v[200:203], v[184:187], v[86:89]
	v_mfma_f32_16x16x32_bf16 v[82:85], v[208:211], v[184:187], v[82:85]
	v_mfma_f32_16x16x32_bf16 v[70:73], v[200:203], v[192:195], v[70:73]
	v_mfma_f32_16x16x32_bf16 v[66:69], v[208:211], v[192:195], v[66:69]
	s_mov_b32 m0, s18
	v_lshl_add_u64 v[176:177], v[212:213], 0, s[24:25]
	s_barrier
	ds_read_b128 v[156:159], v231 offset:49152
	ds_read_b128 v[160:163], v231 offset:50176
	ds_read_b128 v[164:167], v231 offset:51200
	ds_read_b128 v[168:171], v231 offset:52224
	ds_read_b128 v[172:175], v231 offset:53248
	ds_read_b128 v[184:187], v231 offset:54272
	ds_read_b128 v[188:191], v231 offset:55296
	ds_read_b128 v[192:195], v231 offset:56320
	global_load_lds_dwordx4 v[176:177], off
	v_lshl_add_u64 v[176:177], v[214:215], 0, s[24:25]
	s_mov_b32 m0, s19
	s_nop 0
	global_load_lds_dwordx4 v[176:177], off
	s_barrier
	s_waitcnt lgkmcnt(0)
	s_waitcnt lgkmcnt(0)
	v_mfma_f32_16x16x32_bf16 v[62:65], v[130:133], v[156:159], v[62:65]
	v_mfma_f32_16x16x32_bf16 v[58:61], v[138:141], v[156:159], v[58:61]
	v_mfma_f32_16x16x32_bf16 v[46:49], v[130:133], v[164:167], v[46:49]
	v_mfma_f32_16x16x32_bf16 v[42:45], v[138:141], v[164:167], v[42:45]
	v_mfma_f32_16x16x32_bf16 v[30:33], v[130:133], v[172:175], v[30:33]
	v_mfma_f32_16x16x32_bf16 v[26:29], v[138:141], v[172:175], v[26:29]
	v_mfma_f32_16x16x32_bf16 v[14:17], v[130:133], v[188:191], v[14:17]
	v_mfma_f32_16x16x32_bf16 v[10:13], v[138:141], v[188:191], v[10:13]
	v_mfma_f32_16x16x32_bf16 v[62:65], v[134:137], v[160:163], v[62:65]
	v_mfma_f32_16x16x32_bf16 v[58:61], v[142:145], v[160:163], v[58:61]
	v_mfma_f32_16x16x32_bf16 v[46:49], v[134:137], v[168:171], v[46:49]
	v_mfma_f32_16x16x32_bf16 v[42:45], v[142:145], v[168:171], v[42:45]
	v_mfma_f32_16x16x32_bf16 v[30:33], v[134:137], v[184:187], v[30:33]
	v_mfma_f32_16x16x32_bf16 v[26:29], v[142:145], v[184:187], v[26:29]
	v_mfma_f32_16x16x32_bf16 v[14:17], v[134:137], v[192:195], v[14:17]
	v_mfma_f32_16x16x32_bf16 v[10:13], v[142:145], v[192:195], v[10:13]
	s_barrier
	s_add_u32 s6, s62, 0x40080
	s_addc_u32 s7, s63, 0
	s_add_i32 s33, s90, s11
	v_lshl_add_u64 v[130:131], s[6:7], 0, v[146:147]
	s_mov_b32 m0, s33
	s_nop 0
	global_load_lds_dwordx4 v[130:131], off
	v_lshl_add_u64 v[130:131], s[6:7], 0, v[148:149]
	s_add_i32 m0, s33, 0x2000
	s_nop 0
	global_load_lds_dwordx4 v[130:131], off
	s_waitcnt vmcnt(10)
	s_barrier
	v_mfma_f32_16x16x32_bf16 v[54:57], v[196:199], v[156:159], v[54:57]
	v_mfma_f32_16x16x32_bf16 v[50:53], v[204:207], v[156:159], v[50:53]
	v_mfma_f32_16x16x32_bf16 v[38:41], v[196:199], v[164:167], v[38:41]
	v_mfma_f32_16x16x32_bf16 v[34:37], v[204:207], v[164:167], v[34:37]
	v_mfma_f32_16x16x32_bf16 v[22:25], v[196:199], v[172:175], v[22:25]
	v_mfma_f32_16x16x32_bf16 v[18:21], v[204:207], v[172:175], v[18:21]
	v_mfma_f32_16x16x32_bf16 v[6:9], v[196:199], v[188:191], v[6:9]
	v_mfma_f32_16x16x32_bf16 v[2:5], v[204:207], v[188:191], v[2:5]
	v_mfma_f32_16x16x32_bf16 v[54:57], v[200:203], v[160:163], v[54:57]
	v_mfma_f32_16x16x32_bf16 v[50:53], v[208:211], v[160:163], v[50:53]
	v_mfma_f32_16x16x32_bf16 v[38:41], v[200:203], v[168:171], v[38:41]
	v_mfma_f32_16x16x32_bf16 v[34:37], v[208:211], v[168:171], v[34:37]
	v_mfma_f32_16x16x32_bf16 v[22:25], v[200:203], v[184:187], v[22:25]
	v_mfma_f32_16x16x32_bf16 v[18:21], v[208:211], v[184:187], v[18:21]
	v_mfma_f32_16x16x32_bf16 v[6:9], v[200:203], v[192:195], v[6:9]
	v_mfma_f32_16x16x32_bf16 v[2:5], v[208:211], v[192:195], v[2:5]
	s_add_i32 vcc_hi, vcc_hi, 2
	s_add_u32 s2, s2, 0x100
	s_addc_u32 s3, s3, 0
	s_add_u32 s69, s69, 0x100
	s_addc_u32 vcc_lo, vcc_lo, 0
	s_cmp_gt_u32 vcc_hi, 13
	s_barrier
	s_cbranch_scc0 .LBB0_179
	s_cmp_gt_i32 s72, 17
	s_cbranch_scc0 .LBB0_182
	s_and_b32 s1, s72, 0x7ffffffe
	s_cmp_gt_u32 s72, 25
	s_cselect_b32 s2, 3, 0
	s_cmp_lg_u32 s1, 22
	s_cselect_b32 s1, s2, 4
	s_cmp_eq_u32 s72, 19
	s_cselect_b64 vcc, -1, 0
	v_mov_b32_e32 v0, 0x3e000000
	s_and_b64 s[2:3], vcc, exec
	v_cndmask_b32_e32 v154, 1.0, v0, vcc
	s_cselect_b32 s39, 2, s1
	s_movk_i32 s94, 0x2000
	s_mov_b32 s1, 0
	s_cbranch_execz .LBB0_183
	s_branch .LBB0_188

.LBB0_519:
	s_lshl_b32 s0, s28, 26
	s_add_u32 s0, s18, s0
	s_addc_u32 s1, s19, 0
	s_add_u32 s0, s0, 0x3c00000
	v_lshrrev_b32_e32 v17, 1, v13
	s_addc_u32 s1, s1, 0
	v_and_b32_e32 v17, 24, v17
	s_add_u32 s40, s18, 0x19c00000
	v_and_b32_e32 v16, 15, v13
	v_lshlrev_b32_e32 v18, 1, v17
	v_lshlrev_b32_e32 v13, 2, v13
	s_addc_u32 s41, s19, 0
	s_and_b32 s6, s20, 3
	v_lshl_or_b32 v179, s21, 6, v16
	v_lshl_or_b32 v16, v16, 6, v18
	s_lshl_b32 s7, s21, 13
	v_and_b32_e32 v13, 32, v13
	v_bitop3_b32 v18, v16, s7, v13 bitop3:0xde
	s_lshl_b32 s7, s6, 12
	s_add_i32 m0, s3, 0x18000
	v_lshl_add_u64 v[8:9], v[8:9], 0, s[24:25]
	v_bitop3_b32 v184, v16, s7, v13 bitop3:0xde
	s_waitcnt vmcnt(4)
	s_barrier
	global_load_lds_dwordx4 v[8:9], off
	v_lshl_add_u64 v[6:7], v[6:7], 0, s[24:25]
	s_add_i32 m0, s3, 0x1a000
	s_add_i32 s7, s3, 0x8000
	s_add_i32 s18, s3, 0xa000
	global_load_lds_dwordx4 v[6:7], off
	v_lshl_add_u64 v[4:5], v[4:5], 0, s[24:25]
	s_mov_b32 m0, s7
	s_add_u32 s20, s90, 0x20080
	global_load_lds_dwordx4 v[4:5], off
	v_lshl_add_u64 v[2:3], v[2:3], 0, s[24:25]
	s_mov_b32 m0, s18
	s_addc_u32 s21, s91, 0
	global_load_lds_dwordx4 v[2:3], off
	s_add_i32 m0, s3, 0x1c000
	v_lshl_add_u64 v[2:3], s[20:21], 0, v[162:163]
	global_load_lds_dwordx4 v[2:3], off
	v_lshl_add_u64 v[2:3], s[20:21], 0, v[164:165]
	s_add_i32 m0, s3, 0x1e000
	v_or_b32_e32 v186, 16, v179
	global_load_lds_dwordx4 v[2:3], off
	v_lshlrev_b32_e32 v2, 8, v179
	v_and_b32_e32 v185, 0xcf00, v2
	v_lshlrev_b32_e32 v2, 8, v186
	v_or_b32_e32 v188, 32, v179
	v_and_b32_e32 v187, 0xdf00, v2
	v_lshlrev_b32_e32 v2, 8, v188
	v_or_b32_e32 v190, 48, v179
	v_and_b32_e32 v189, 0xef00, v2
	v_lshlrev_b32_e32 v2, 8, v190
	v_add_u32_e32 v192, 0x80, v179
	v_and_b32_e32 v191, 0xff00, v2
	v_lshlrev_b32_e32 v2, 8, v192
	v_add_u32_e32 v194, 0x90, v179
	v_and_b32_e32 v193, 0xcf00, v2
	v_lshlrev_b32_e32 v2, 8, v194
	v_add_u32_e32 v196, 0xa0, v179
	v_and_b32_e32 v195, 0xdf00, v2
	v_lshlrev_b32_e32 v2, 8, v196
	v_add_u32_e32 v198, 0xb0, v179
	v_and_b32_e32 v197, 0xef00, v2
	v_lshlrev_b32_e32 v2, 8, v198
	v_and_b32_e32 v199, 0xff00, v2
	v_lshlrev_b32_e32 v2, 13, v0
	v_and_b32_e32 v2, 0xffffc000, v2
	v_lshl_add_u32 v2, v10, 10, v2
	v_and_b32_e32 v0, 1, v0
	v_lshl_or_b32 v0, v0, 6, v2
	v_lshl_add_u32 v166, v11, 1, v0
	v_lshlrev_b32_e32 v0, 13, v12
	v_and_b32_e32 v0, 0xffffc000, v0
	s_waitcnt vmcnt(6)
	v_lshl_add_u32 v0, v14, 10, v0
	v_and_b32_e32 v2, 1, v12
	v_lshl_or_b32 v0, v2, 6, v0
	s_ashr_i32 s19, s8, 31
	v_lshl_or_b32 v200, s6, 6, v17
	v_mov_b32_e32 v167, v1
	v_lshl_add_u32 v168, v15, 1, v0
	v_mov_b32_e32 v169, v1
	s_mov_b32 s20, 0
	v_add_u32_e32 v201, 0, v18
	s_barrier
	s_branch .LBB0_521
	s_nop 0
	s_nop 0
	s_nop 0
	s_nop 0
	s_nop 0
	s_nop 0
	s_nop 0
	s_nop 0

.LBB0_528:
	s_add_u32 s6, s62, 0xfffe0080
	s_addc_u32 s33, s63, -1
	s_add_i32 s72, 0, 0x10000
	v_add_u32_e32 v0, s72, v184
	ds_read_b128 v[130:133], v0
	ds_read_b128 v[134:137], v0 offset:1024
	ds_read_b128 v[138:141], v0 offset:2048
	ds_read_b128 v[142:145], v0 offset:3072
	s_cmp_eq_u32 s69, 4
	s_cselect_b32 vcc_hi, s21, s33
	s_cselect_b32 vcc_lo, s22, s6
	s_cselect_b32 s91, s23, s48
	s_cselect_b32 s90, s39, s47
	v_lshl_add_u64 v[180:181], s[62:63], 0, v[166:167]
	s_add_i32 m0, s3, 0xc000
	ds_read_b128 v[146:149], v201
	ds_read_b128 v[150:153], v201 offset:1024
	ds_read_b128 v[154:157], v201 offset:2048
	ds_read_b128 v[158:161], v201 offset:3072
	ds_read_b128 v[170:173], v201 offset:4096
	ds_read_b128 v[174:177], v201 offset:5120
	ds_read_b128 v[202:205], v201 offset:6144
	ds_read_b128 v[206:209], v201 offset:7168
	global_load_lds_dwordx4 v[180:181], off
	v_lshl_add_u64 v[180:181], s[62:63], 0, v[168:169]
	s_add_i32 m0, s3, 0xe000
	s_nop 0
	global_load_lds_dwordx4 v[180:181], off
	s_waitcnt lgkmcnt(8)
	s_waitcnt vmcnt(10)
	s_barrier
	s_waitcnt lgkmcnt(0)
	s_waitcnt lgkmcnt(0)
	v_mfma_f32_16x16x32_bf16 v[126:129], v[130:133], v[146:149], v[126:129]
	v_mfma_f32_16x16x32_bf16 v[122:125], v[138:141], v[146:149], v[122:125]
	v_mfma_f32_16x16x32_bf16 v[110:113], v[130:133], v[154:157], v[110:113]
	v_mfma_f32_16x16x32_bf16 v[106:109], v[138:141], v[154:157], v[106:109]
	v_mfma_f32_16x16x32_bf16 v[94:97], v[130:133], v[170:173], v[94:97]
	v_mfma_f32_16x16x32_bf16 v[90:93], v[138:141], v[170:173], v[90:93]
	v_mfma_f32_16x16x32_bf16 v[78:81], v[130:133], v[202:205], v[78:81]
	v_mfma_f32_16x16x32_bf16 v[74:77], v[138:141], v[202:205], v[74:77]
	v_mfma_f32_16x16x32_bf16 v[126:129], v[134:137], v[150:153], v[126:129]
	v_mfma_f32_16x16x32_bf16 v[122:125], v[142:145], v[150:153], v[122:125]
	v_mfma_f32_16x16x32_bf16 v[110:113], v[134:137], v[158:161], v[110:113]
	v_mfma_f32_16x16x32_bf16 v[106:109], v[142:145], v[158:161], v[106:109]
	v_mfma_f32_16x16x32_bf16 v[94:97], v[134:137], v[174:177], v[94:97]
	v_mfma_f32_16x16x32_bf16 v[90:93], v[142:145], v[174:177], v[90:93]
	v_mfma_f32_16x16x32_bf16 v[78:81], v[134:137], v[206:209], v[78:81]
	v_mfma_f32_16x16x32_bf16 v[74:77], v[142:145], v[206:209], v[74:77]
	s_barrier
	s_add_i32 s6, 0, 0x14000
	s_add_i32 s33, s72, s14
	v_add_u32_e32 v0, s6, v184
	v_lshl_add_u64 v[180:181], s[90:91], 0, v[162:163]
	s_mov_b32 m0, s33
	ds_read_b128 v[210:213], v0
	ds_read_b128 v[214:217], v0 offset:1024
	ds_read_b128 v[218:221], v0 offset:2048
	ds_read_b128 v[222:225], v0 offset:3072
	global_load_lds_dwordx4 v[180:181], off
	v_lshl_add_u64 v[226:227], s[90:91], 0, v[164:165]
	s_add_i32 m0, s33, 0x2000
	s_nop 0
	global_load_lds_dwordx4 v[226:227], off
	s_waitcnt vmcnt(10)
	s_barrier
	s_waitcnt lgkmcnt(0)
	s_waitcnt lgkmcnt(0)
	v_mfma_f32_16x16x32_bf16 v[118:121], v[210:213], v[146:149], v[118:121]
	v_mfma_f32_16x16x32_bf16 v[114:117], v[218:221], v[146:149], v[114:117]
	v_mfma_f32_16x16x32_bf16 v[102:105], v[210:213], v[154:157], v[102:105]
	v_mfma_f32_16x16x32_bf16 v[98:101], v[218:221], v[154:157], v[98:101]
	v_mfma_f32_16x16x32_bf16 v[86:89], v[210:213], v[170:173], v[86:89]
	v_mfma_f32_16x16x32_bf16 v[82:85], v[218:221], v[170:173], v[82:85]
	v_mfma_f32_16x16x32_bf16 v[70:73], v[210:213], v[202:205], v[70:73]
	v_mfma_f32_16x16x32_bf16 v[66:69], v[218:221], v[202:205], v[66:69]
	v_mfma_f32_16x16x32_bf16 v[118:121], v[214:217], v[150:153], v[118:121]
	v_mfma_f32_16x16x32_bf16 v[114:117], v[222:225], v[150:153], v[114:117]
	v_mfma_f32_16x16x32_bf16 v[102:105], v[214:217], v[158:161], v[102:105]
	v_mfma_f32_16x16x32_bf16 v[98:101], v[222:225], v[158:161], v[98:101]
	v_mfma_f32_16x16x32_bf16 v[86:89], v[214:217], v[174:177], v[86:89]
	v_mfma_f32_16x16x32_bf16 v[82:85], v[222:225], v[174:177], v[82:85]
	v_mfma_f32_16x16x32_bf16 v[70:73], v[214:217], v[206:209], v[70:73]
	v_mfma_f32_16x16x32_bf16 v[66:69], v[222:225], v[206:209], v[66:69]
	s_mov_b32 m0, s3
	v_lshl_add_u64 v[240:241], vcc, 0, v[162:163]
	s_barrier
	ds_read_b128 v[146:149], v201 offset:16384
	ds_read_b128 v[150:153], v201 offset:17408
	ds_read_b128 v[154:157], v201 offset:18432
	ds_read_b128 v[158:161], v201 offset:19456
	ds_read_b128 v[170:173], v201 offset:20480
	ds_read_b128 v[174:177], v201 offset:21504
	ds_read_b128 v[202:205], v201 offset:22528
	ds_read_b128 v[206:209], v201 offset:23552
	global_load_lds_dwordx4 v[240:241], off
	v_lshl_add_u64 v[244:245], vcc, 0, v[164:165]
	s_mov_b32 m0, s15
	s_nop 0
	global_load_lds_dwordx4 v[244:245], off
	s_barrier
	s_waitcnt lgkmcnt(0)
	s_waitcnt lgkmcnt(0)
	v_mfma_f32_16x16x32_bf16 v[62:65], v[130:133], v[146:149], v[62:65]
	v_mfma_f32_16x16x32_bf16 v[58:61], v[138:141], v[146:149], v[58:61]
	v_mfma_f32_16x16x32_bf16 v[46:49], v[130:133], v[154:157], v[46:49]
	v_mfma_f32_16x16x32_bf16 v[42:45], v[138:141], v[154:157], v[42:45]
	v_mfma_f32_16x16x32_bf16 v[30:33], v[130:133], v[170:173], v[30:33]
	v_mfma_f32_16x16x32_bf16 v[26:29], v[138:141], v[170:173], v[26:29]
	v_mfma_f32_16x16x32_bf16 v[14:17], v[130:133], v[202:205], v[14:17]
	v_mfma_f32_16x16x32_bf16 v[10:13], v[138:141], v[202:205], v[10:13]
	v_mfma_f32_16x16x32_bf16 v[62:65], v[134:137], v[150:153], v[62:65]
	v_mfma_f32_16x16x32_bf16 v[58:61], v[142:145], v[150:153], v[58:61]
	v_mfma_f32_16x16x32_bf16 v[46:49], v[134:137], v[158:161], v[46:49]
	v_mfma_f32_16x16x32_bf16 v[42:45], v[142:145], v[158:161], v[42:45]
	v_mfma_f32_16x16x32_bf16 v[30:33], v[134:137], v[174:177], v[30:33]
	v_mfma_f32_16x16x32_bf16 v[26:29], v[142:145], v[174:177], v[26:29]
	v_mfma_f32_16x16x32_bf16 v[14:17], v[134:137], v[206:209], v[14:17]
	v_mfma_f32_16x16x32_bf16 v[10:13], v[142:145], v[206:209], v[10:13]
	s_barrier
	s_add_u32 s72, s90, 0x20000
	s_addc_u32 s73, s91, 0
	s_add_i32 s6, s6, s14
	v_lshl_add_u64 v[130:131], s[72:73], 0, v[162:163]
	s_mov_b32 m0, s6
	s_nop 0
	global_load_lds_dwordx4 v[130:131], off
	v_lshl_add_u64 v[130:131], s[72:73], 0, v[164:165]
	s_add_i32 m0, s6, 0x2000
	s_nop 0
	global_load_lds_dwordx4 v[130:131], off
	s_waitcnt vmcnt(10)
	s_barrier
	v_mfma_f32_16x16x32_bf16 v[54:57], v[210:213], v[146:149], v[54:57]
	v_mfma_f32_16x16x32_bf16 v[50:53], v[218:221], v[146:149], v[50:53]
	v_mfma_f32_16x16x32_bf16 v[38:41], v[210:213], v[154:157], v[38:41]
	v_mfma_f32_16x16x32_bf16 v[34:37], v[218:221], v[154:157], v[34:37]
	v_mfma_f32_16x16x32_bf16 v[22:25], v[210:213], v[170:173], v[22:25]
	v_mfma_f32_16x16x32_bf16 v[18:21], v[218:221], v[170:173], v[18:21]
	v_mfma_f32_16x16x32_bf16 v[6:9], v[210:213], v[202:205], v[6:9]
	v_mfma_f32_16x16x32_bf16 v[2:5], v[218:221], v[202:205], v[2:5]
	v_mfma_f32_16x16x32_bf16 v[54:57], v[214:217], v[150:153], v[54:57]
	v_mfma_f32_16x16x32_bf16 v[50:53], v[222:225], v[150:153], v[50:53]
	v_mfma_f32_16x16x32_bf16 v[38:41], v[214:217], v[158:161], v[38:41]
	v_mfma_f32_16x16x32_bf16 v[34:37], v[222:225], v[158:161], v[34:37]
	v_mfma_f32_16x16x32_bf16 v[22:25], v[214:217], v[174:177], v[22:25]
	v_mfma_f32_16x16x32_bf16 v[18:21], v[222:225], v[174:177], v[18:21]
	v_mfma_f32_16x16x32_bf16 v[6:9], v[214:217], v[206:209], v[6:9]
	v_mfma_f32_16x16x32_bf16 v[2:5], v[222:225], v[206:209], v[2:5]
	s_add_i32 s6, 0, 0x18000
	v_add_u32_e32 v0, s6, v184
	s_barrier
	ds_read_b128 v[130:133], v0
	ds_read_b128 v[134:137], v0 offset:1024
	ds_read_b128 v[138:141], v0 offset:2048
	ds_read_b128 v[142:145], v0 offset:3072
	s_add_u32 s72, vcc_lo, 0x20000
	s_addc_u32 s73, vcc_hi, 0
	s_mov_b32 m0, s16
	v_lshl_add_u64 v[210:211], s[72:73], 0, v[162:163]
	ds_read_b128 v[146:149], v201 offset:32768
	ds_read_b128 v[150:153], v201 offset:33792
	ds_read_b128 v[154:157], v201 offset:34816
	ds_read_b128 v[158:161], v201 offset:35840
	ds_read_b128 v[170:173], v201 offset:36864
	ds_read_b128 v[174:177], v201 offset:37888
	ds_read_b128 v[202:205], v201 offset:38912
	ds_read_b128 v[206:209], v201 offset:39936
	global_load_lds_dwordx4 v[210:211], off
	v_lshl_add_u64 v[210:211], s[72:73], 0, v[164:165]
	s_mov_b32 m0, s17
	s_nop 0
	global_load_lds_dwordx4 v[210:211], off
	s_waitcnt lgkmcnt(8)
	s_waitcnt vmcnt(10)
	s_barrier
	s_waitcnt lgkmcnt(0)
	s_waitcnt lgkmcnt(0)
	v_mfma_f32_16x16x32_bf16 v[126:129], v[130:133], v[146:149], v[126:129]
	v_mfma_f32_16x16x32_bf16 v[122:125], v[138:141], v[146:149], v[122:125]
	v_mfma_f32_16x16x32_bf16 v[110:113], v[130:133], v[154:157], v[110:113]
	v_mfma_f32_16x16x32_bf16 v[106:109], v[138:141], v[154:157], v[106:109]
	v_mfma_f32_16x16x32_bf16 v[94:97], v[130:133], v[170:173], v[94:97]
	v_mfma_f32_16x16x32_bf16 v[90:93], v[138:141], v[170:173], v[90:93]
	v_mfma_f32_16x16x32_bf16 v[78:81], v[130:133], v[202:205], v[78:81]
	v_mfma_f32_16x16x32_bf16 v[74:77], v[138:141], v[202:205], v[74:77]
	v_mfma_f32_16x16x32_bf16 v[126:129], v[134:137], v[150:153], v[126:129]
	v_mfma_f32_16x16x32_bf16 v[122:125], v[142:145], v[150:153], v[122:125]
	v_mfma_f32_16x16x32_bf16 v[110:113], v[134:137], v[158:161], v[110:113]
	v_mfma_f32_16x16x32_bf16 v[106:109], v[142:145], v[158:161], v[106:109]
	v_mfma_f32_16x16x32_bf16 v[94:97], v[134:137], v[174:177], v[94:97]
	v_mfma_f32_16x16x32_bf16 v[90:93], v[142:145], v[174:177], v[90:93]
	v_mfma_f32_16x16x32_bf16 v[78:81], v[134:137], v[206:209], v[78:81]
	v_mfma_f32_16x16x32_bf16 v[74:77], v[142:145], v[206:209], v[74:77]
	s_barrier
	s_add_i32 s33, 0, 0x1c000
	s_add_i32 s6, s6, s14
	v_add_u32_e32 v0, s33, v184
	v_lshl_add_u64 v[180:181], v[180:181], 0, s[24:25]
	s_mov_b32 m0, s6
	ds_read_b128 v[210:213], v0
	ds_read_b128 v[214:217], v0 offset:1024
	ds_read_b128 v[218:221], v0 offset:2048
	ds_read_b128 v[222:225], v0 offset:3072
	global_load_lds_dwordx4 v[180:181], off
	v_lshl_add_u64 v[180:181], v[226:227], 0, s[24:25]
	s_add_i32 m0, s6, 0x2000
	s_nop 0
	global_load_lds_dwordx4 v[180:181], off
	s_waitcnt vmcnt(10)
	s_barrier
	s_waitcnt lgkmcnt(0)
	s_waitcnt lgkmcnt(0)
	v_mfma_f32_16x16x32_bf16 v[118:121], v[210:213], v[146:149], v[118:121]
	v_mfma_f32_16x16x32_bf16 v[114:117], v[218:221], v[146:149], v[114:117]
	v_mfma_f32_16x16x32_bf16 v[102:105], v[210:213], v[154:157], v[102:105]
	v_mfma_f32_16x16x32_bf16 v[98:101], v[218:221], v[154:157], v[98:101]
	v_mfma_f32_16x16x32_bf16 v[86:89], v[210:213], v[170:173], v[86:89]
	v_mfma_f32_16x16x32_bf16 v[82:85], v[218:221], v[170:173], v[82:85]
	v_mfma_f32_16x16x32_bf16 v[70:73], v[210:213], v[202:205], v[70:73]
	v_mfma_f32_16x16x32_bf16 v[66:69], v[218:221], v[202:205], v[66:69]
	v_mfma_f32_16x16x32_bf16 v[118:121], v[214:217], v[150:153], v[118:121]
	v_mfma_f32_16x16x32_bf16 v[114:117], v[222:225], v[150:153], v[114:117]
	v_mfma_f32_16x16x32_bf16 v[102:105], v[214:217], v[158:161], v[102:105]
	v_mfma_f32_16x16x32_bf16 v[98:101], v[222:225], v[158:161], v[98:101]
	v_mfma_f32_16x16x32_bf16 v[86:89], v[214:217], v[174:177], v[86:89]
	v_mfma_f32_16x16x32_bf16 v[82:85], v[222:225], v[174:177], v[82:85]
	v_mfma_f32_16x16x32_bf16 v[70:73], v[214:217], v[206:209], v[70:73]
	v_mfma_f32_16x16x32_bf16 v[66:69], v[222:225], v[206:209], v[66:69]
	s_mov_b32 m0, s7
	v_lshl_add_u64 v[180:181], v[240:241], 0, s[24:25]
	s_barrier
	ds_read_b128 v[146:149], v201 offset:49152
	ds_read_b128 v[150:153], v201 offset:50176
	ds_read_b128 v[154:157], v201 offset:51200
	ds_read_b128 v[158:161], v201 offset:52224
	ds_read_b128 v[170:173], v201 offset:53248
	ds_read_b128 v[174:177], v201 offset:54272
	ds_read_b128 v[202:205], v201 offset:55296
	ds_read_b128 v[206:209], v201 offset:56320
	global_load_lds_dwordx4 v[180:181], off
	v_lshl_add_u64 v[180:181], v[244:245], 0, s[24:25]
	s_mov_b32 m0, s18
	s_nop 0
	global_load_lds_dwordx4 v[180:181], off
	s_barrier
	s_waitcnt lgkmcnt(0)
	s_waitcnt lgkmcnt(0)
	v_mfma_f32_16x16x32_bf16 v[62:65], v[130:133], v[146:149], v[62:65]
	v_mfma_f32_16x16x32_bf16 v[58:61], v[138:141], v[146:149], v[58:61]
	v_mfma_f32_16x16x32_bf16 v[46:49], v[130:133], v[154:157], v[46:49]
	v_mfma_f32_16x16x32_bf16 v[42:45], v[138:141], v[154:157], v[42:45]
	v_mfma_f32_16x16x32_bf16 v[30:33], v[130:133], v[170:173], v[30:33]
	v_mfma_f32_16x16x32_bf16 v[26:29], v[138:141], v[170:173], v[26:29]
	v_mfma_f32_16x16x32_bf16 v[14:17], v[130:133], v[202:205], v[14:17]
	v_mfma_f32_16x16x32_bf16 v[10:13], v[138:141], v[202:205], v[10:13]
	v_mfma_f32_16x16x32_bf16 v[62:65], v[134:137], v[150:153], v[62:65]
	v_mfma_f32_16x16x32_bf16 v[58:61], v[142:145], v[150:153], v[58:61]
	v_mfma_f32_16x16x32_bf16 v[46:49], v[134:137], v[158:161], v[46:49]
	v_mfma_f32_16x16x32_bf16 v[42:45], v[142:145], v[158:161], v[42:45]
	v_mfma_f32_16x16x32_bf16 v[30:33], v[134:137], v[174:177], v[30:33]
	v_mfma_f32_16x16x32_bf16 v[26:29], v[142:145], v[174:177], v[26:29]
	v_mfma_f32_16x16x32_bf16 v[14:17], v[134:137], v[206:209], v[14:17]
	v_mfma_f32_16x16x32_bf16 v[10:13], v[142:145], v[206:209], v[10:13]
	s_barrier
	s_add_u32 s72, s90, 0x20080
	s_addc_u32 s73, s91, 0
	s_add_i32 s6, s33, s14
	v_lshl_add_u64 v[130:131], s[72:73], 0, v[162:163]
	s_mov_b32 m0, s6
	s_nop 0
	global_load_lds_dwordx4 v[130:131], off
	v_lshl_add_u64 v[130:131], s[72:73], 0, v[164:165]
	s_add_i32 m0, s6, 0x2000
	s_nop 0
	global_load_lds_dwordx4 v[130:131], off
	s_waitcnt vmcnt(10)
	s_barrier
	v_mfma_f32_16x16x32_bf16 v[54:57], v[210:213], v[146:149], v[54:57]
	v_mfma_f32_16x16x32_bf16 v[50:53], v[218:221], v[146:149], v[50:53]
	v_mfma_f32_16x16x32_bf16 v[38:41], v[210:213], v[154:157], v[38:41]
	v_mfma_f32_16x16x32_bf16 v[34:37], v[218:221], v[154:157], v[34:37]
	v_mfma_f32_16x16x32_bf16 v[22:25], v[210:213], v[170:173], v[22:25]
	v_mfma_f32_16x16x32_bf16 v[18:21], v[218:221], v[170:173], v[18:21]
	v_mfma_f32_16x16x32_bf16 v[6:9], v[210:213], v[202:205], v[6:9]
	v_mfma_f32_16x16x32_bf16 v[2:5], v[218:221], v[202:205], v[2:5]
	v_mfma_f32_16x16x32_bf16 v[54:57], v[214:217], v[150:153], v[54:57]
	v_mfma_f32_16x16x32_bf16 v[50:53], v[222:225], v[150:153], v[50:53]
	v_mfma_f32_16x16x32_bf16 v[38:41], v[214:217], v[158:161], v[38:41]
	v_mfma_f32_16x16x32_bf16 v[34:37], v[222:225], v[158:161], v[34:37]
	v_mfma_f32_16x16x32_bf16 v[22:25], v[214:217], v[174:177], v[22:25]
	v_mfma_f32_16x16x32_bf16 v[18:21], v[222:225], v[174:177], v[18:21]
	v_mfma_f32_16x16x32_bf16 v[6:9], v[214:217], v[206:209], v[6:9]
	v_mfma_f32_16x16x32_bf16 v[2:5], v[222:225], v[206:209], v[2:5]
	s_add_i32 s69, s69, 2
	s_add_u32 s62, s62, 0x100
	s_addc_u32 s63, s63, 0
	s_add_u32 s47, s47, 0x100
	s_addc_u32 s48, s48, 0
	s_cmp_gt_u32 s69, 5
	s_barrier
	s_cbranch_scc0 .LBB0_528
	s_lshl_b32 s21, s38, 8
	s_ashr_i32 s6, s38, 2
	s_and_b32 s21, s21, 0x300
	s_cmp_lt_u32 s38, 4
	s_cselect_b64 s[62:63], -1, 0
	s_cmp_gt_u32 s38, 3
	s_cselect_b64 s[90:91], -1, 0
	s_lshl_b32 s22, s6, 15
	s_lshl_b32 s2, s2, 8
	s_lshl_b32 s6, s6, 10
	v_or_b32_e32 v132, s21, v200
	s_sub_i32 s2, s2, s22
	s_addk_i32 s6, 0x1a00
	v_add_u32_e32 v0, s6, v132
	v_add_u32_e32 v170, s2, v179
	v_ashrrev_i32_e32 v203, 8, v0
	v_lshrrev_b32_e32 v0, 8, v170
	v_mad_i32_i24 v130, v0, 38, v203
	v_bitop3_b32 v202, s21, v243, v200 bitop3:0xc8
	v_ashrrev_i32_e32 v131, 31, v130
	v_or_b32_e32 v0, v202, v185
	v_lshlrev_b64 v[130:131], 17, v[130:131]
	v_lshl_add_u64 v[130:131], s[40:41], 0, v[130:131]
	v_lshlrev_b32_e32 v0, 1, v0
	v_lshl_add_u64 v[130:131], v[130:131], 0, v[0:1]
	global_load_dwordx4 v[154:157], v[130:131], off
	global_load_dwordx4 v[138:141], v[130:131], off offset:64
	v_lshlrev_b32_e32 v172, 1, v132
	v_mov_b32_e32 v173, v1
	v_lshl_add_u64 v[176:177], s[0:1], 0, v[172:173]
	v_mov_b32_e32 v130, 0
	s_and_b64 vcc, exec, s[62:63]
	v_ashrrev_i32_e32 v171, 31, v170
	v_mov_b32_e32 v146, 0
	v_mov_b32_e32 v147, 0
	v_mov_b32_e32 v148, 0
	v_mov_b32_e32 v149, 0
	v_mov_b32_e32 v158, 0
	v_mov_b32_e32 v159, 0
	v_mov_b32_e32 v160, 0
	v_mov_b32_e32 v161, 0
	s_cbranch_vccnz .LBB0_531
	v_lshlrev_b64 v[132:133], 11, v[170:171]
	v_lshl_add_u64 v[132:133], v[176:177], 0, v[132:133]
	global_load_dwordx4 v[158:161], v[132:133], off
	global_load_dwordx4 v[146:149], v[132:133], off offset:64

.LBB0_609:
	s_add_u32 s24, s16, 0x19c00000
	s_addc_u32 s25, s17, 0
	v_bfe_u32 v16, v8, 4, 2
	s_add_u32 s26, s16, 0x12000000
	v_and_b32_e32 v15, 15, v8
	v_lshlrev_b32_e32 v18, 4, v16
	v_lshlrev_b32_e32 v8, 2, v8
	s_addc_u32 s27, s17, 0
	s_and_b32 s3, s18, 3
	v_lshl_or_b32 v182, s19, 6, v15
	v_lshl_or_b32 v15, v15, 6, v18
	s_lshl_b32 s16, s19, 13
	v_and_b32_e32 v8, 32, v8
	s_mov_b64 s[28:29], 0x80
	v_bitop3_b32 v18, v15, s16, v8 bitop3:0xde
	s_lshl_b32 s16, s3, 12
	s_add_i32 m0, s11, 0x18000
	v_lshl_add_u64 v[6:7], v[6:7], 0, s[28:29]
	v_bitop3_b32 v183, v15, s16, v8 bitop3:0xde
	s_waitcnt vmcnt(4)
	s_barrier
	global_load_lds_dwordx4 v[6:7], off
	v_lshl_add_u64 v[4:5], v[4:5], 0, s[28:29]
	s_add_i32 m0, s11, 0x1a000
	s_add_i32 s16, s11, 0x8000
	s_add_i32 s17, s11, 0xa000
	global_load_lds_dwordx4 v[4:5], off
	v_lshl_add_u64 v[2:3], v[2:3], 0, s[28:29]
	s_mov_b32 m0, s16
	s_add_u32 s18, s52, 0x40080
	global_load_lds_dwordx4 v[2:3], off
	v_lshl_add_u64 v[0:1], v[0:1], 0, s[28:29]
	s_mov_b32 m0, s17
	s_addc_u32 s19, s53, 0
	global_load_lds_dwordx4 v[0:1], off
	s_add_i32 m0, s11, 0x1c000
	v_lshl_add_u64 v[0:1], s[18:19], 0, v[160:161]
	global_load_lds_dwordx4 v[0:1], off
	v_lshl_add_u64 v[0:1], s[18:19], 0, v[162:163]
	s_add_i32 m0, s11, 0x1e000
	v_lshlrev_b32_e32 v17, 3, v16
	global_load_lds_dwordx4 v[0:1], off
	v_lshlrev_b32_e32 v0, 14, v9
	v_and_b32_e32 v0, 0xffff8000, v0
	v_lshl_add_u32 v0, v10, 11, v0
	v_and_b32_e32 v1, 1, v9
	v_lshl_or_b32 v0, v1, 6, v0
	v_lshl_add_u32 v164, v11, 1, v0
	v_lshlrev_b32_e32 v0, 14, v12
	v_and_b32_e32 v0, 0xffff8000, v0
	s_waitcnt vmcnt(6)
	v_lshl_add_u32 v0, v13, 11, v0
	v_and_b32_e32 v1, 1, v12
	v_lshl_or_b32 v0, v1, 6, v0
	s_add_i32 s19, 0, 0x10000
	s_add_i32 s20, 0, 0x14000
	v_lshl_or_b32 v184, s3, 6, v17
	v_cmp_eq_u32_e64 s[36:37], 0, v16
	s_ashr_i32 s18, s4, 31
	v_mov_b32_e32 v165, v161
	v_lshl_add_u32 v166, v14, 1, v0
	v_mov_b32_e32 v167, v161
	v_mov_b64_e32 v[168:169], 0x400
	v_mov_b64_e32 v[170:171], 0x3ff
	v_add_u32_e32 v185, s19, v183
	v_add_u32_e32 v186, 0, v18
	v_add_u32_e32 v187, s20, v183
	s_barrier
	s_branch .LBB0_611
	s_nop 0
	s_nop 0
	s_nop 0
	s_nop 0
	s_nop 0
	s_nop 0
	s_nop 0
	s_nop 0
	s_nop 0
	s_nop 0
	s_nop 0
	s_nop 0

.LBB0_618:
	ds_read_b128 v[48:51], v185
	ds_read_b128 v[52:55], v185 offset:1024
	ds_read_b128 v[56:59], v185 offset:2048
	ds_read_b128 v[60:63], v185 offset:3072
	s_add_u32 s47, s48, 0xfffc0080
	s_addc_u32 s50, s49, -1
	s_cmp_eq_u32 s35, 12
	s_cselect_b32 s55, s3, s50
	s_cselect_b32 s54, s21, s47
	s_cselect_b32 s53, s22, s33
	s_cselect_b32 s52, s23, s31
	v_lshl_add_u64 v[180:181], s[48:49], 0, v[164:165]
	s_add_i32 m0, s11, 0xc000
	ds_read_b128 v[144:147], v186
	ds_read_b128 v[148:151], v186 offset:1024
	ds_read_b128 v[152:155], v186 offset:2048
	ds_read_b128 v[156:159], v186 offset:3072
	ds_read_b128 v[172:175], v186 offset:4096
	ds_read_b128 v[176:179], v186 offset:5120
	ds_read_b128 v[188:191], v186 offset:6144
	ds_read_b128 v[192:195], v186 offset:7168
	global_load_lds_dwordx4 v[180:181], off
	v_lshl_add_u64 v[180:181], s[48:49], 0, v[166:167]
	s_add_i32 m0, s11, 0xe000
	s_nop 0
	global_load_lds_dwordx4 v[180:181], off
	s_waitcnt lgkmcnt(8)
	s_waitcnt vmcnt(10)
	s_barrier
	s_waitcnt lgkmcnt(0)
	s_waitcnt lgkmcnt(0)
	v_mfma_f32_16x16x32_bf16 v[140:143], v[48:51], v[144:147], v[140:143]
	v_mfma_f32_16x16x32_bf16 v[136:139], v[56:59], v[144:147], v[136:139]
	v_mfma_f32_16x16x32_bf16 v[124:127], v[48:51], v[152:155], v[124:127]
	v_mfma_f32_16x16x32_bf16 v[120:123], v[56:59], v[152:155], v[120:123]
	v_mfma_f32_16x16x32_bf16 v[108:111], v[48:51], v[172:175], v[108:111]
	v_mfma_f32_16x16x32_bf16 v[104:107], v[56:59], v[172:175], v[104:107]
	v_mfma_f32_16x16x32_bf16 v[92:95], v[48:51], v[188:191], v[92:95]
	v_mfma_f32_16x16x32_bf16 v[88:91], v[56:59], v[188:191], v[88:91]
	v_mfma_f32_16x16x32_bf16 v[140:143], v[52:55], v[148:151], v[140:143]
	v_mfma_f32_16x16x32_bf16 v[136:139], v[60:63], v[148:151], v[136:139]
	v_mfma_f32_16x16x32_bf16 v[124:127], v[52:55], v[156:159], v[124:127]
	v_mfma_f32_16x16x32_bf16 v[120:123], v[60:63], v[156:159], v[120:123]
	v_mfma_f32_16x16x32_bf16 v[108:111], v[52:55], v[176:179], v[108:111]
	v_mfma_f32_16x16x32_bf16 v[104:107], v[60:63], v[176:179], v[104:107]
	v_mfma_f32_16x16x32_bf16 v[92:95], v[52:55], v[192:195], v[92:95]
	v_mfma_f32_16x16x32_bf16 v[88:91], v[60:63], v[192:195], v[88:91]
	s_barrier
	s_add_i32 s47, s19, s10
	v_lshl_add_u64 v[180:181], s[52:53], 0, v[160:161]
	s_mov_b32 m0, s47
	ds_read_b128 v[196:199], v187
	ds_read_b128 v[200:203], v187 offset:1024
	ds_read_b128 v[204:207], v187 offset:2048
	ds_read_b128 v[208:211], v187 offset:3072
	global_load_lds_dwordx4 v[180:181], off
	v_lshl_add_u64 v[212:213], s[52:53], 0, v[162:163]
	s_add_i32 m0, s47, 0x2000
	s_nop 0
	global_load_lds_dwordx4 v[212:213], off
	s_waitcnt vmcnt(10)
	s_barrier
	s_waitcnt lgkmcnt(0)
	s_waitcnt lgkmcnt(0)
	v_mfma_f32_16x16x32_bf16 v[132:135], v[196:199], v[144:147], v[132:135]
	v_mfma_f32_16x16x32_bf16 v[128:131], v[204:207], v[144:147], v[128:131]
	v_mfma_f32_16x16x32_bf16 v[116:119], v[196:199], v[152:155], v[116:119]
	v_mfma_f32_16x16x32_bf16 v[112:115], v[204:207], v[152:155], v[112:115]
	v_mfma_f32_16x16x32_bf16 v[100:103], v[196:199], v[172:175], v[100:103]
	v_mfma_f32_16x16x32_bf16 v[96:99], v[204:207], v[172:175], v[96:99]
	v_mfma_f32_16x16x32_bf16 v[84:87], v[196:199], v[188:191], v[84:87]
	v_mfma_f32_16x16x32_bf16 v[80:83], v[204:207], v[188:191], v[80:83]
	v_mfma_f32_16x16x32_bf16 v[132:135], v[200:203], v[148:151], v[132:135]
	v_mfma_f32_16x16x32_bf16 v[128:131], v[208:211], v[148:151], v[128:131]
	v_mfma_f32_16x16x32_bf16 v[116:119], v[200:203], v[156:159], v[116:119]
	v_mfma_f32_16x16x32_bf16 v[112:115], v[208:211], v[156:159], v[112:115]
	v_mfma_f32_16x16x32_bf16 v[100:103], v[200:203], v[176:179], v[100:103]
	v_mfma_f32_16x16x32_bf16 v[96:99], v[208:211], v[176:179], v[96:99]
	v_mfma_f32_16x16x32_bf16 v[84:87], v[200:203], v[192:195], v[84:87]
	v_mfma_f32_16x16x32_bf16 v[80:83], v[208:211], v[192:195], v[80:83]
	s_mov_b32 m0, s11
	v_lshl_add_u64 v[214:215], s[54:55], 0, v[160:161]
	s_barrier
	ds_read_b128 v[144:147], v186 offset:16384
	ds_read_b128 v[148:151], v186 offset:17408
	ds_read_b128 v[152:155], v186 offset:18432
	ds_read_b128 v[156:159], v186 offset:19456
	ds_read_b128 v[172:175], v186 offset:20480
	ds_read_b128 v[176:179], v186 offset:21504
	ds_read_b128 v[188:191], v186 offset:22528
	ds_read_b128 v[192:195], v186 offset:23552
	global_load_lds_dwordx4 v[214:215], off
	v_lshl_add_u64 v[216:217], s[54:55], 0, v[162:163]
	s_mov_b32 m0, s12
	s_nop 0
	global_load_lds_dwordx4 v[216:217], off
	s_barrier
	s_waitcnt lgkmcnt(0)
	s_waitcnt lgkmcnt(0)
	v_mfma_f32_16x16x32_bf16 v[76:79], v[48:51], v[144:147], v[76:79]
	v_mfma_f32_16x16x32_bf16 v[72:75], v[56:59], v[144:147], v[72:75]
	v_mfma_f32_16x16x32_bf16 v[44:47], v[48:51], v[152:155], v[44:47]
	v_mfma_f32_16x16x32_bf16 v[40:43], v[56:59], v[152:155], v[40:43]
	v_mfma_f32_16x16x32_bf16 v[28:31], v[48:51], v[172:175], v[28:31]
	v_mfma_f32_16x16x32_bf16 v[24:27], v[56:59], v[172:175], v[24:27]
	v_mfma_f32_16x16x32_bf16 v[12:15], v[48:51], v[188:191], v[12:15]
	v_mfma_f32_16x16x32_bf16 v[8:11], v[56:59], v[188:191], v[8:11]
	v_mfma_f32_16x16x32_bf16 v[76:79], v[52:55], v[148:151], v[76:79]
	v_mfma_f32_16x16x32_bf16 v[72:75], v[60:63], v[148:151], v[72:75]
	v_mfma_f32_16x16x32_bf16 v[44:47], v[52:55], v[156:159], v[44:47]
	v_mfma_f32_16x16x32_bf16 v[40:43], v[60:63], v[156:159], v[40:43]
	v_mfma_f32_16x16x32_bf16 v[28:31], v[52:55], v[176:179], v[28:31]
	v_mfma_f32_16x16x32_bf16 v[24:27], v[60:63], v[176:179], v[24:27]
	v_mfma_f32_16x16x32_bf16 v[12:15], v[52:55], v[192:195], v[12:15]
	v_mfma_f32_16x16x32_bf16 v[8:11], v[60:63], v[192:195], v[8:11]
	s_barrier
	s_add_u32 s50, s52, 0x40000
	s_addc_u32 s51, s53, 0
	s_add_i32 s47, s20, s10
	v_lshl_add_u64 v[48:49], s[50:51], 0, v[160:161]
	s_mov_b32 m0, s47
	s_nop 0
	global_load_lds_dwordx4 v[48:49], off
	v_lshl_add_u64 v[48:49], s[50:51], 0, v[162:163]
	s_add_i32 m0, s47, 0x2000
	s_nop 0
	global_load_lds_dwordx4 v[48:49], off
	s_waitcnt vmcnt(10)
	s_barrier
	v_mfma_f32_16x16x32_bf16 v[36:39], v[196:199], v[152:155], v[36:39]
	v_mfma_f32_16x16x32_bf16 v[32:35], v[204:207], v[152:155], v[32:35]
	v_mfma_f32_16x16x32_bf16 v[20:23], v[196:199], v[172:175], v[20:23]
	v_mfma_f32_16x16x32_bf16 v[16:19], v[204:207], v[172:175], v[16:19]
	v_mfma_f32_16x16x32_bf16 v[4:7], v[196:199], v[188:191], v[4:7]
	v_mfma_f32_16x16x32_bf16 v[0:3], v[204:207], v[188:191], v[0:3]
	v_mfma_f32_16x16x32_bf16 v[48:51], v[196:199], v[144:147], v[68:71]
	v_mfma_f32_16x16x32_bf16 v[52:55], v[204:207], v[144:147], v[64:67]
	v_mfma_f32_16x16x32_bf16 v[36:39], v[200:203], v[156:159], v[36:39]
	v_mfma_f32_16x16x32_bf16 v[32:35], v[208:211], v[156:159], v[32:35]
	v_mfma_f32_16x16x32_bf16 v[20:23], v[200:203], v[176:179], v[20:23]
	v_mfma_f32_16x16x32_bf16 v[16:19], v[208:211], v[176:179], v[16:19]
	v_mfma_f32_16x16x32_bf16 v[4:7], v[200:203], v[192:195], v[4:7]
	v_mfma_f32_16x16x32_bf16 v[0:3], v[208:211], v[192:195], v[0:3]
	v_mfma_f32_16x16x32_bf16 v[48:51], v[200:203], v[148:151], v[48:51]
	v_mfma_f32_16x16x32_bf16 v[52:55], v[208:211], v[148:151], v[52:55]
	s_add_i32 s47, 0, 0x18000
	v_add_u32_e32 v68, s47, v183
	s_barrier
	ds_read_b128 v[56:59], v68
	ds_read_b128 v[60:63], v68 offset:1024
	ds_read_b128 v[64:67], v68 offset:2048
	ds_read_b128 v[68:71], v68 offset:3072
	s_add_u32 s50, s54, 0x40000
	s_addc_u32 s51, s55, 0
	s_mov_b32 m0, s13
	v_lshl_add_u64 v[196:197], s[50:51], 0, v[160:161]
	ds_read_b128 v[144:147], v186 offset:32768
	ds_read_b128 v[148:151], v186 offset:33792
	ds_read_b128 v[152:155], v186 offset:34816
	ds_read_b128 v[156:159], v186 offset:35840
	ds_read_b128 v[172:175], v186 offset:36864
	ds_read_b128 v[176:179], v186 offset:37888
	ds_read_b128 v[188:191], v186 offset:38912
	ds_read_b128 v[192:195], v186 offset:39936
	global_load_lds_dwordx4 v[196:197], off
	v_lshl_add_u64 v[196:197], s[50:51], 0, v[162:163]
	s_mov_b32 m0, s14
	s_nop 0
	global_load_lds_dwordx4 v[196:197], off
	s_waitcnt lgkmcnt(8)
	s_waitcnt vmcnt(10)
	s_barrier
	s_waitcnt lgkmcnt(0)
	s_waitcnt lgkmcnt(0)
	v_mfma_f32_16x16x32_bf16 v[140:143], v[56:59], v[144:147], v[140:143]
	v_mfma_f32_16x16x32_bf16 v[136:139], v[64:67], v[144:147], v[136:139]
	v_mfma_f32_16x16x32_bf16 v[124:127], v[56:59], v[152:155], v[124:127]
	v_mfma_f32_16x16x32_bf16 v[120:123], v[64:67], v[152:155], v[120:123]
	v_mfma_f32_16x16x32_bf16 v[108:111], v[56:59], v[172:175], v[108:111]
	v_mfma_f32_16x16x32_bf16 v[104:107], v[64:67], v[172:175], v[104:107]
	v_mfma_f32_16x16x32_bf16 v[92:95], v[56:59], v[188:191], v[92:95]
	v_mfma_f32_16x16x32_bf16 v[88:91], v[64:67], v[188:191], v[88:91]
	v_mfma_f32_16x16x32_bf16 v[140:143], v[60:63], v[148:151], v[140:143]
	v_mfma_f32_16x16x32_bf16 v[136:139], v[68:71], v[148:151], v[136:139]
	v_mfma_f32_16x16x32_bf16 v[124:127], v[60:63], v[156:159], v[124:127]
	v_mfma_f32_16x16x32_bf16 v[120:123], v[68:71], v[156:159], v[120:123]
	v_mfma_f32_16x16x32_bf16 v[108:111], v[60:63], v[176:179], v[108:111]
	v_mfma_f32_16x16x32_bf16 v[104:107], v[68:71], v[176:179], v[104:107]
	v_mfma_f32_16x16x32_bf16 v[92:95], v[60:63], v[192:195], v[92:95]
	v_mfma_f32_16x16x32_bf16 v[88:91], v[68:71], v[192:195], v[88:91]
	s_barrier
	s_add_i32 s54, 0, 0x1c000
	s_add_i32 s47, s47, s10
	v_add_u32_e32 v208, s54, v183
	v_lshl_add_u64 v[180:181], v[180:181], 0, s[28:29]
	s_mov_b32 m0, s47
	ds_read_b128 v[196:199], v208
	ds_read_b128 v[200:203], v208 offset:1024
	ds_read_b128 v[204:207], v208 offset:2048
	ds_read_b128 v[208:211], v208 offset:3072
	global_load_lds_dwordx4 v[180:181], off
	v_lshl_add_u64 v[180:181], v[212:213], 0, s[28:29]
	s_add_i32 m0, s47, 0x2000
	s_nop 0
	global_load_lds_dwordx4 v[180:181], off
	s_waitcnt vmcnt(10)
	s_barrier
	s_waitcnt lgkmcnt(0)
	s_waitcnt lgkmcnt(0)
	v_mfma_f32_16x16x32_bf16 v[132:135], v[196:199], v[144:147], v[132:135]
	v_mfma_f32_16x16x32_bf16 v[128:131], v[204:207], v[144:147], v[128:131]
	v_mfma_f32_16x16x32_bf16 v[116:119], v[196:199], v[152:155], v[116:119]
	v_mfma_f32_16x16x32_bf16 v[112:115], v[204:207], v[152:155], v[112:115]
	v_mfma_f32_16x16x32_bf16 v[100:103], v[196:199], v[172:175], v[100:103]
	v_mfma_f32_16x16x32_bf16 v[96:99], v[204:207], v[172:175], v[96:99]
	v_mfma_f32_16x16x32_bf16 v[84:87], v[196:199], v[188:191], v[84:87]
	v_mfma_f32_16x16x32_bf16 v[80:83], v[204:207], v[188:191], v[80:83]
	v_mfma_f32_16x16x32_bf16 v[132:135], v[200:203], v[148:151], v[132:135]
	v_mfma_f32_16x16x32_bf16 v[128:131], v[208:211], v[148:151], v[128:131]
	v_mfma_f32_16x16x32_bf16 v[116:119], v[200:203], v[156:159], v[116:119]
	v_mfma_f32_16x16x32_bf16 v[112:115], v[208:211], v[156:159], v[112:115]
	v_mfma_f32_16x16x32_bf16 v[100:103], v[200:203], v[176:179], v[100:103]
	v_mfma_f32_16x16x32_bf16 v[96:99], v[208:211], v[176:179], v[96:99]
	v_mfma_f32_16x16x32_bf16 v[84:87], v[200:203], v[192:195], v[84:87]
	v_mfma_f32_16x16x32_bf16 v[80:83], v[208:211], v[192:195], v[80:83]
	s_mov_b32 m0, s16
	v_lshl_add_u64 v[180:181], v[214:215], 0, s[28:29]
	s_barrier
	ds_read_b128 v[144:147], v186 offset:49152
	ds_read_b128 v[148:151], v186 offset:50176
	ds_read_b128 v[152:155], v186 offset:51200
	ds_read_b128 v[156:159], v186 offset:52224
	ds_read_b128 v[172:175], v186 offset:53248
	ds_read_b128 v[176:179], v186 offset:54272
	ds_read_b128 v[188:191], v186 offset:55296
	ds_read_b128 v[192:195], v186 offset:56320
	global_load_lds_dwordx4 v[180:181], off
	v_lshl_add_u64 v[180:181], v[216:217], 0, s[28:29]
	s_mov_b32 m0, s17
	s_nop 0
	global_load_lds_dwordx4 v[180:181], off
	s_barrier
	s_waitcnt lgkmcnt(0)
	s_waitcnt lgkmcnt(0)
	v_mfma_f32_16x16x32_bf16 v[76:79], v[56:59], v[144:147], v[76:79]
	v_mfma_f32_16x16x32_bf16 v[72:75], v[64:67], v[144:147], v[72:75]
	v_mfma_f32_16x16x32_bf16 v[44:47], v[56:59], v[152:155], v[44:47]
	v_mfma_f32_16x16x32_bf16 v[40:43], v[64:67], v[152:155], v[40:43]
	v_mfma_f32_16x16x32_bf16 v[28:31], v[56:59], v[172:175], v[28:31]
	v_mfma_f32_16x16x32_bf16 v[24:27], v[64:67], v[172:175], v[24:27]
	v_mfma_f32_16x16x32_bf16 v[12:15], v[56:59], v[188:191], v[12:15]
	v_mfma_f32_16x16x32_bf16 v[8:11], v[64:67], v[188:191], v[8:11]
	v_mfma_f32_16x16x32_bf16 v[76:79], v[60:63], v[148:151], v[76:79]
	v_mfma_f32_16x16x32_bf16 v[72:75], v[68:71], v[148:151], v[72:75]
	v_mfma_f32_16x16x32_bf16 v[44:47], v[60:63], v[156:159], v[44:47]
	v_mfma_f32_16x16x32_bf16 v[40:43], v[68:71], v[156:159], v[40:43]
	v_mfma_f32_16x16x32_bf16 v[28:31], v[60:63], v[176:179], v[28:31]
	v_mfma_f32_16x16x32_bf16 v[24:27], v[68:71], v[176:179], v[24:27]
	v_mfma_f32_16x16x32_bf16 v[12:15], v[60:63], v[192:195], v[12:15]
	v_mfma_f32_16x16x32_bf16 v[8:11], v[68:71], v[192:195], v[8:11]
	s_barrier
	s_add_u32 s50, s52, 0x40080
	s_addc_u32 s51, s53, 0
	s_add_i32 s47, s54, s10
	v_lshl_add_u64 v[56:57], s[50:51], 0, v[160:161]
	s_mov_b32 m0, s47
	s_nop 0
	global_load_lds_dwordx4 v[56:57], off
	v_lshl_add_u64 v[56:57], s[50:51], 0, v[162:163]
	s_add_i32 m0, s47, 0x2000
	s_nop 0
	global_load_lds_dwordx4 v[56:57], off
	s_waitcnt vmcnt(10)
	s_barrier
	v_mfma_f32_16x16x32_bf16 v[48:51], v[196:199], v[144:147], v[48:51]
	v_mfma_f32_16x16x32_bf16 v[68:71], v[200:203], v[148:151], v[48:51]
	v_mfma_f32_16x16x32_bf16 v[48:51], v[204:207], v[144:147], v[52:55]
	v_mfma_f32_16x16x32_bf16 v[36:39], v[196:199], v[152:155], v[36:39]
	v_mfma_f32_16x16x32_bf16 v[32:35], v[204:207], v[152:155], v[32:35]
	v_mfma_f32_16x16x32_bf16 v[20:23], v[196:199], v[172:175], v[20:23]
	v_mfma_f32_16x16x32_bf16 v[16:19], v[204:207], v[172:175], v[16:19]
	v_mfma_f32_16x16x32_bf16 v[4:7], v[196:199], v[188:191], v[4:7]
	v_mfma_f32_16x16x32_bf16 v[0:3], v[204:207], v[188:191], v[0:3]
	v_mfma_f32_16x16x32_bf16 v[64:67], v[208:211], v[148:151], v[48:51]
	v_mfma_f32_16x16x32_bf16 v[36:39], v[200:203], v[156:159], v[36:39]
	v_mfma_f32_16x16x32_bf16 v[32:35], v[208:211], v[156:159], v[32:35]
	v_mfma_f32_16x16x32_bf16 v[20:23], v[200:203], v[176:179], v[20:23]
	v_mfma_f32_16x16x32_bf16 v[16:19], v[208:211], v[176:179], v[16:19]
	v_mfma_f32_16x16x32_bf16 v[4:7], v[200:203], v[192:195], v[4:7]
	v_mfma_f32_16x16x32_bf16 v[0:3], v[208:211], v[192:195], v[0:3]
	s_add_i32 s35, s35, 2
	s_add_u32 s48, s48, 0x100
	s_addc_u32 s49, s49, 0
	s_add_u32 s31, s31, 0x100
	s_addc_u32 s33, s33, 0
	s_cmp_gt_u32 s35, 13
	s_barrier
	s_cbranch_scc0 .LBB0_618
	v_and_b32_e32 v145, 64, v229
	v_xor_b32_e32 v144, 16, v229
	v_add_u32_e32 v145, 64, v145
	v_cmp_lt_i32_e32 vcc, v144, v145
	v_lshl_or_b32 v172, s46, 8, v184
	v_ashrrev_i32_e32 v173, 31, v172
	v_cndmask_b32_e32 v144, v229, v144, vcc
	v_lshl_add_u32 v174, s2, 8, v182
	v_lshlrev_b32_e32 v189, 2, v144
	v_xor_b32_e32 v144, 32, v229
	v_lshlrev_b64 v[206:207], 2, v[172:173]
	v_cmp_lt_i32_e32 vcc, v144, v145
	v_ashrrev_i32_e32 v175, 31, v174
	v_lshl_add_u64 v[176:177], s[44:45], 0, v[206:207]
	v_cndmask_b32_e32 v144, v229, v144, vcc
	v_lshlrev_b64 v[208:209], 12, v[174:175]
	v_lshl_add_u64 v[56:57], s[56:57], 0, v[206:207]
	v_lshlrev_b32_e32 v188, 2, v144
	v_lshl_add_u64 v[144:145], v[176:177], 0, v[208:209]
	global_load_dwordx4 v[52:55], v[56:57], off offset:16
	global_load_dwordx4 v[60:63], v[56:57], off
	global_load_dwordx4 v[48:51], v[56:57], off offset:144
	s_nop 0
	global_load_dwordx4 v[56:59], v[56:57], off offset:128
	s_nop 0
	global_load_dwordx4 v[190:193], v[144:145], off offset:16
	global_load_dwordx4 v[194:197], v[144:145], off
	global_load_dwordx4 v[198:201], v[144:145], off offset:144
	global_load_dwordx4 v[202:205], v[144:145], off offset:128
	v_or_b32_e32 v178, 16, v174
	v_ashrrev_i32_e32 v179, 31, v178
	v_lshlrev_b64 v[180:181], 12, v[178:179]
	v_lshl_add_u64 v[148:149], v[176:177], 0, v[180:181]
	global_load_dwordx4 v[152:155], v[148:149], off offset:16
	global_load_dwordx4 v[156:159], v[148:149], off
	global_load_dwordx4 v[144:147], v[148:149], off offset:144
	s_nop 0
	global_load_dwordx4 v[148:151], v[148:149], off offset:128
	s_waitcnt vmcnt(0)
	v_pk_add_f32 v[136:137], v[136:137], v[190:191]
	v_pk_add_f32 v[194:195], v[140:141], v[194:195]
	v_pk_add_f32 v[198:199], v[128:129], v[198:199]
	v_lshl_add_u64 v[128:129], s[78:79], 0, v[208:209]
	v_pk_add_f32 v[196:197], v[142:143], v[196:197]
	v_pk_mul_f32 v[212:213], v[194:195], v[194:195]
	v_pk_add_f32 v[190:191], v[132:133], v[202:203]
	v_lshl_add_u64 v[128:129], v[128:129], 0, v[206:207]
	v_pk_mul_f32 v[210:211], v[196:197], v[196:197]
	v_pk_add_f32 v[138:139], v[138:139], v[192:193]
	v_pk_add_f32 v[192:193], v[134:135], v[204:205]
	v_pk_mul_f32 v[204:205], v[190:191], v[190:191]
	v_pk_add_f32 v[200:201], v[130:131], v[200:201]
	global_store_dwordx4 v[128:129], v[194:197], off nt
	global_store_dwordx4 v[128:129], v[136:139], off offset:16 nt
	global_store_dwordx4 v[128:129], v[190:193], off offset:128 nt
	global_store_dwordx4 v[128:129], v[198:201], off offset:144 nt
	v_pk_mul_f32 v[134:135], v[56:57], v[190:191]
	v_add_f32_e32 v190, v212, v213
	v_add_f32_e32 v190, v210, v190
	v_pk_mul_f32 v[216:217], v[136:137], v[136:137]
	v_add_f32_e32 v190, v211, v190
	v_add_f32_e32 v190, v216, v190
	v_pk_mul_f32 v[214:215], v[138:139], v[138:139]
	v_add_f32_e32 v190, v217, v190
	v_add_f32_e32 v190, v214, v190
	v_add_f32_e32 v190, v215, v190
	v_add_f32_e32 v190, v204, v190
	v_pk_mul_f32 v[202:203], v[192:193], v[192:193]
	v_add_f32_e32 v190, v205, v190
	v_add_f32_e32 v190, v202, v190
	v_pk_mul_f32 v[220:221], v[198:199], v[198:199]
	v_add_f32_e32 v190, v203, v190
	v_add_f32_e32 v190, v220, v190
	v_pk_mul_f32 v[218:219], v[200:201], v[200:201]
	v_add_f32_e32 v190, v221, v190
	v_add_f32_e32 v190, v218, v190
	v_pk_mul_f32 v[128:129], v[62:63], v[196:197]
	v_add_f32_e32 v196, v219, v190
	v_lshlrev_b64 v[190:191], 11, v[174:175]
	v_pk_mul_f32 v[142:143], v[60:61], v[194:195]
	v_pk_mul_f32 v[130:131], v[52:53], v[136:137]
	v_pk_mul_f32 v[132:133], v[54:55], v[138:139]
	v_lshl_add_u64 v[190:191], s[24:25], 0, v[190:191]
	v_pk_mul_f32 v[136:137], v[58:59], v[192:193]
	v_pk_mul_f32 v[138:139], v[48:49], v[198:199]
	v_pk_mul_f32 v[140:141], v[50:51], v[200:201]
	v_lshl_add_u64 v[194:195], v[172:173], 1, v[190:191]
	v_cvt_pk_bf16_f32 v190, v142, v143
	v_cvt_pk_bf16_f32 v191, v128, v129
	v_cvt_pk_bf16_f32 v192, v130, v131
	v_cvt_pk_bf16_f32 v193, v132, v133
	v_cvt_pk_bf16_f32 v128, v134, v135
	v_cvt_pk_bf16_f32 v129, v136, v137
	v_cvt_pk_bf16_f32 v130, v138, v139
	v_cvt_pk_bf16_f32 v131, v140, v141
	global_store_dwordx4 v[194:195], v[190:193], off nt
	global_store_dwordx4 v[194:195], v[128:131], off offset:64 nt
	ds_bpermute_b32 v128, v189, v196
	s_waitcnt lgkmcnt(0)
	v_add_f32_e32 v128, v196, v128
	ds_bpermute_b32 v129, v188, v128
	s_and_saveexec_b64 s[2:3], s[36:37]
	s_cbranch_execz .LBB0_621
	v_lshl_add_u64 v[130:131], v[174:175], 2, s[26:27]
	s_waitcnt lgkmcnt(0)
	v_add_f32_e32 v128, v128, v129
	global_atomic_add_f32 v[130:131], v128, off

.LBB0_698:
	v_readlane_b32 s20, v254, 1
	v_readlane_b32 s21, v254, 2
	v_readlane_b32 s22, v254, 3
	v_readlane_b32 s23, v254, 4
	v_readlane_b32 s24, v254, 5
	v_readlane_b32 s25, v254, 6
	v_readlane_b32 s26, v254, 7
	v_readlane_b32 s27, v254, 8
	s_mov_b64 s[20:21], s[24:25]
	s_add_u32 s96, s20, 0x2c00
	s_addc_u32 s97, s21, 0
	s_add_u32 s86, s20, 0x5800
	s_addc_u32 s87, s21, 0
	s_add_u32 s28, s2, 0x21c00000
	s_addc_u32 s29, s3, 0
	s_add_u32 s30, s2, 0x14000000
	v_lshrrev_b32_e32 v16, 1, v8
	s_addc_u32 s31, s3, 0
	v_and_b32_e32 v16, 24, v16
	s_add_u32 s34, s2, 0x12000000
	v_and_b32_e32 v15, 15, v8
	v_lshlrev_b32_e32 v17, 1, v16
	v_lshlrev_b32_e32 v18, 2, v8
	s_addc_u32 s35, s3, 0
	v_lshl_or_b32 v17, v15, 6, v17
	s_lshl_b32 s2, s10, 13
	v_and_b32_e32 v18, 32, v18
	v_bitop3_b32 v19, v17, s2, v18 bitop3:0xde
	s_lshl_b32 s2, s17, 5
	s_mov_b64 s[52:53], 0x80
	s_and_b32 s20, s2, 0x60
	s_add_i32 m0, s12, 0x18000
	v_lshl_add_u64 v[6:7], v[6:7], 0, s[52:53]
	s_lshl_b32 s2, s20, 7
	s_waitcnt vmcnt(4)
	s_barrier
	global_load_lds_dwordx4 v[6:7], off
	v_lshl_add_u64 v[4:5], v[4:5], 0, s[52:53]
	s_add_i32 m0, s12, 0x1a000
	s_add_i32 s17, s12, 0x8000
	s_add_i32 s18, s12, 0xa000
	v_bitop3_b32 v232, v17, s2, v18 bitop3:0xde
	global_load_lds_dwordx4 v[4:5], off
	v_lshl_add_u64 v[2:3], v[2:3], 0, s[52:53]
	s_mov_b32 m0, s17
	s_add_u32 s2, s0, 0x40080
	global_load_lds_dwordx4 v[2:3], off
	v_lshl_add_u64 v[0:1], v[0:1], 0, s[52:53]
	s_mov_b32 m0, s18
	s_addc_u32 s3, s1, 0
	global_load_lds_dwordx4 v[0:1], off
	s_add_i32 m0, s12, 0x1c000
	v_lshl_add_u64 v[0:1], s[2:3], 0, v[160:161]
	global_load_lds_dwordx4 v[0:1], off
	v_lshl_add_u64 v[0:1], s[2:3], 0, v[162:163]
	s_add_i32 m0, s12, 0x1e000
	v_cmp_eq_u32_e64 s[38:39], 15, v15
	global_load_lds_dwordx4 v[0:1], off
	s_nop 0
	v_cndmask_b32_e64 v0, -1, 3, s[38:39]
	v_cmp_ne_u32_e32 vcc, 14, v15
	v_cmp_eq_u32_e64 s[42:43], 0, v15
	v_and_b32_e32 v1, 1, v9
	v_cndmask_b32_e32 v233, 2, v0, vcc
	v_cmp_eq_u32_e32 vcc, 1, v15
	s_waitcnt vmcnt(6)
	v_or_b32_e32 v235, s20, v16
	s_add_i32 s20, 0, 0x10000
	v_cndmask_b32_e64 v0, -1, 1, vcc
	v_cndmask_b32_e64 v234, v0, 0, s[42:43]
	v_and_b32_e32 v0, 14, v8
	v_cmp_eq_u32_e64 s[74:75], 14, v0
	v_lshlrev_b32_e32 v0, 14, v9
	v_and_b32_e32 v0, 0xffff8000, v0
	v_lshl_add_u32 v0, v10, 11, v0
	v_lshl_or_b32 v0, v1, 6, v0
	v_lshl_add_u32 v166, v11, 1, v0
	v_lshlrev_b32_e32 v0, 14, v12
	v_and_b32_e32 v0, 0xffff8000, v0
	v_lshl_add_u32 v0, v13, 11, v0
	v_and_b32_e32 v1, 1, v12
	v_lshl_or_b32 v0, v1, 6, v0
	s_add_i32 s21, 0, 0x14000
	v_lshl_or_b32 v231, s10, 6, v15
	v_cmp_ne_u32_e64 s[36:37], 15, v15
	v_cmp_ne_u32_e64 s[40:41], 0, v15
	v_cmp_gt_u32_e64 s[70:71], 2, v15
	s_ashr_i32 s19, s4, 31
	v_mov_b32_e32 v167, v165
	v_lshl_add_u32 v168, v14, 1, v0
	v_mov_b32_e32 v169, v165
	v_mov_b64_e32 v[170:171], 0x1600
	v_mov_b64_e32 v[172:173], 0x15ff
	v_add_u32_e32 v236, s20, v232
	v_add_u32_e32 v237, 0, v19
	v_add_u32_e32 v238, s21, v232
	v_mov_b32_e32 v239, 0x358637bd
	s_mov_b32 s33, 0x800000
	s_movk_i32 s65, 0xb00
	s_mov_b32 s54, 0xbf38aa3b
	s_mov_b32 s56, 0x3e6d3388
	s_mov_b32 s58, 0x3f07dc22
	s_mov_b32 s64, 0xbf3a00e3
	s_mov_b32 s66, 0x3f35f0e3
	s_mov_b32 s68, 0xbe11a98e
	s_mov_b32 s72, 0x3e027906
	s_mov_b64 s[22:23], s[26:27]
	s_barrier
	s_branch .LBB0_700
	s_nop 0
	s_nop 0
	s_nop 0
	s_nop 0
	s_nop 0
	s_nop 0
	s_nop 0
	s_nop 0
	s_nop 0
	s_nop 0
	s_nop 0
	s_nop 0

.LBB0_703:
	ds_read_b128 v[44:47], v236
	ds_read_b128 v[48:51], v236 offset:1024
	ds_read_b128 v[52:55], v236 offset:2048
	ds_read_b128 v[56:59], v236 offset:3072
	s_add_u32 s0, vcc_lo, 0xfffc0080
	s_addc_u32 s1, vcc_hi, -1
	s_cmp_eq_u32 s59, 12
	s_cselect_b32 s91, s22, s1
	s_cselect_b32 s90, s23, s0
	s_cselect_b32 s1, s3, s57
	s_cselect_b32 s0, s51, s55
	v_lshl_add_u64 v[190:191], vcc, 0, v[166:167]
	s_add_i32 m0, s12, 0xc000
	ds_read_b128 v[68:71], v237
	ds_read_b128 v[72:75], v237 offset:1024
	ds_read_b128 v[76:79], v237 offset:2048
	ds_read_b128 v[80:83], v237 offset:3072
	ds_read_b128 v[174:177], v237 offset:4096
	ds_read_b128 v[178:181], v237 offset:5120
	ds_read_b128 v[182:185], v237 offset:6144
	ds_read_b128 v[186:189], v237 offset:7168
	global_load_lds_dwordx4 v[190:191], off
	v_lshl_add_u64 v[190:191], vcc, 0, v[168:169]
	s_add_i32 m0, s12, 0xe000
	s_nop 0
	global_load_lds_dwordx4 v[190:191], off
	s_waitcnt lgkmcnt(8)
	s_waitcnt vmcnt(10)
	s_barrier
	s_waitcnt lgkmcnt(0)
	s_waitcnt lgkmcnt(0)
	v_mfma_f32_16x16x32_bf16 v[156:159], v[44:47], v[68:71], v[156:159]
	v_mfma_f32_16x16x32_bf16 v[132:135], v[52:55], v[68:71], v[132:135]
	v_mfma_f32_16x16x32_bf16 v[152:155], v[44:47], v[76:79], v[152:155]
	v_mfma_f32_16x16x32_bf16 v[128:131], v[52:55], v[76:79], v[128:131]
	v_mfma_f32_16x16x32_bf16 v[140:143], v[44:47], v[174:177], v[140:143]
	v_mfma_f32_16x16x32_bf16 v[104:107], v[52:55], v[174:177], v[104:107]
	v_mfma_f32_16x16x32_bf16 v[144:147], v[44:47], v[182:185], v[144:147]
	v_mfma_f32_16x16x32_bf16 v[108:111], v[52:55], v[182:185], v[108:111]
	v_mfma_f32_16x16x32_bf16 v[156:159], v[48:51], v[72:75], v[156:159]
	v_mfma_f32_16x16x32_bf16 v[132:135], v[56:59], v[72:75], v[132:135]
	v_mfma_f32_16x16x32_bf16 v[152:155], v[48:51], v[80:83], v[152:155]
	v_mfma_f32_16x16x32_bf16 v[128:131], v[56:59], v[80:83], v[128:131]
	v_mfma_f32_16x16x32_bf16 v[140:143], v[48:51], v[178:181], v[140:143]
	v_mfma_f32_16x16x32_bf16 v[104:107], v[56:59], v[178:181], v[104:107]
	v_mfma_f32_16x16x32_bf16 v[144:147], v[48:51], v[186:189], v[144:147]
	v_mfma_f32_16x16x32_bf16 v[108:111], v[56:59], v[186:189], v[108:111]
	s_barrier
	s_add_i32 s60, s20, s11
	v_lshl_add_u64 v[214:215], s[0:1], 0, v[160:161]
	s_mov_b32 m0, s60
	ds_read_b128 v[190:193], v238
	ds_read_b128 v[194:197], v238 offset:1024
	ds_read_b128 v[198:201], v238 offset:2048
	ds_read_b128 v[202:205], v238 offset:3072
	global_load_lds_dwordx4 v[214:215], off
	v_lshl_add_u64 v[216:217], s[0:1], 0, v[162:163]
	s_add_i32 m0, s60, 0x2000
	s_nop 0
	global_load_lds_dwordx4 v[216:217], off
	s_waitcnt vmcnt(10)
	s_barrier
	s_waitcnt lgkmcnt(0)
	s_waitcnt lgkmcnt(0)
	v_mfma_f32_16x16x32_bf16 v[148:151], v[190:193], v[68:71], v[148:151]
	v_mfma_f32_16x16x32_bf16 v[68:71], v[198:201], v[68:71], v[124:127]
	v_mfma_f32_16x16x32_bf16 v[148:151], v[194:197], v[72:75], v[148:151]
	v_mfma_f32_16x16x32_bf16 v[68:71], v[202:205], v[72:75], v[68:71]
	v_mfma_f32_16x16x32_bf16 v[72:75], v[190:193], v[76:79], v[120:123]
	v_mfma_f32_16x16x32_bf16 v[76:79], v[198:201], v[76:79], v[112:115]
	v_mfma_f32_16x16x32_bf16 v[100:103], v[198:201], v[174:177], v[100:103]
	v_mfma_f32_16x16x32_bf16 v[112:115], v[190:193], v[182:185], v[136:139]
	v_mfma_f32_16x16x32_bf16 v[96:99], v[198:201], v[182:185], v[96:99]
	v_mfma_f32_16x16x32_bf16 v[72:75], v[194:197], v[80:83], v[72:75]
	v_mfma_f32_16x16x32_bf16 v[76:79], v[202:205], v[80:83], v[76:79]
	v_mfma_f32_16x16x32_bf16 v[80:83], v[190:193], v[174:177], v[116:119]
	v_mfma_f32_16x16x32_bf16 v[100:103], v[202:205], v[178:181], v[100:103]
	v_mfma_f32_16x16x32_bf16 v[136:139], v[194:197], v[186:189], v[112:115]
	v_mfma_f32_16x16x32_bf16 v[96:99], v[202:205], v[186:189], v[96:99]
	v_mfma_f32_16x16x32_bf16 v[80:83], v[194:197], v[178:181], v[80:83]
	s_mov_b32 m0, s12
	v_lshl_add_u64 v[218:219], s[90:91], 0, v[160:161]
	s_barrier
	ds_read_b128 v[112:115], v237 offset:16384
	ds_read_b128 v[116:119], v237 offset:17408
	ds_read_b128 v[120:123], v237 offset:18432
	ds_read_b128 v[124:127], v237 offset:19456
	ds_read_b128 v[174:177], v237 offset:20480
	ds_read_b128 v[178:181], v237 offset:21504
	ds_read_b128 v[182:185], v237 offset:22528
	ds_read_b128 v[186:189], v237 offset:23552
	global_load_lds_dwordx4 v[218:219], off
	v_lshl_add_u64 v[220:221], s[90:91], 0, v[162:163]
	s_mov_b32 m0, s13
	s_nop 0
	global_load_lds_dwordx4 v[220:221], off
	s_barrier
	s_waitcnt lgkmcnt(0)
	s_waitcnt lgkmcnt(0)
	v_mfma_f32_16x16x32_bf16 v[92:95], v[44:47], v[112:115], v[92:95]
	v_mfma_f32_16x16x32_bf16 v[40:43], v[52:55], v[112:115], v[40:43]
	v_mfma_f32_16x16x32_bf16 v[88:91], v[44:47], v[120:123], v[88:91]
	v_mfma_f32_16x16x32_bf16 v[36:39], v[52:55], v[120:123], v[36:39]
	v_mfma_f32_16x16x32_bf16 v[60:63], v[44:47], v[174:177], v[60:63]
	v_mfma_f32_16x16x32_bf16 v[8:11], v[52:55], v[174:177], v[8:11]
	v_mfma_f32_16x16x32_bf16 v[16:19], v[52:55], v[182:185], v[16:19]
	v_mfma_f32_16x16x32_bf16 v[92:95], v[48:51], v[116:119], v[92:95]
	v_mfma_f32_16x16x32_bf16 v[40:43], v[56:59], v[116:119], v[40:43]
	v_mfma_f32_16x16x32_bf16 v[88:91], v[48:51], v[124:127], v[88:91]
	v_mfma_f32_16x16x32_bf16 v[36:39], v[56:59], v[124:127], v[36:39]
	v_mfma_f32_16x16x32_bf16 v[60:63], v[48:51], v[178:181], v[60:63]
	v_mfma_f32_16x16x32_bf16 v[8:11], v[56:59], v[178:181], v[8:11]
	v_mfma_f32_16x16x32_bf16 v[44:47], v[44:47], v[182:185], v[64:67]
	v_mfma_f32_16x16x32_bf16 v[16:19], v[56:59], v[186:189], v[16:19]
	v_mfma_f32_16x16x32_bf16 v[44:47], v[48:51], v[186:189], v[44:47]
	s_barrier
	s_add_u32 s60, s0, 0x40000
	s_addc_u32 s61, s1, 0
	s_add_i32 s63, s21, s11
	v_lshl_add_u64 v[48:49], s[60:61], 0, v[160:161]
	s_mov_b32 m0, s63
	s_nop 0
	global_load_lds_dwordx4 v[48:49], off
	v_lshl_add_u64 v[48:49], s[60:61], 0, v[162:163]
	s_add_i32 m0, s63, 0x2000
	s_nop 0
	global_load_lds_dwordx4 v[48:49], off
	s_waitcnt vmcnt(10)
	s_barrier
	v_mfma_f32_16x16x32_bf16 v[28:31], v[198:201], v[112:115], v[28:31]
	v_mfma_f32_16x16x32_bf16 v[24:27], v[190:193], v[120:123], v[24:27]
	v_mfma_f32_16x16x32_bf16 v[12:15], v[198:201], v[120:123], v[12:15]
	v_mfma_f32_16x16x32_bf16 v[20:23], v[190:193], v[174:177], v[20:23]
	v_mfma_f32_16x16x32_bf16 v[4:7], v[198:201], v[174:177], v[4:7]
	v_mfma_f32_16x16x32_bf16 v[32:35], v[190:193], v[182:185], v[32:35]
	v_mfma_f32_16x16x32_bf16 v[0:3], v[198:201], v[182:185], v[0:3]
	v_mfma_f32_16x16x32_bf16 v[48:51], v[190:193], v[112:115], v[84:87]
	v_mfma_f32_16x16x32_bf16 v[28:31], v[202:205], v[116:119], v[28:31]
	v_mfma_f32_16x16x32_bf16 v[24:27], v[194:197], v[124:127], v[24:27]
	v_mfma_f32_16x16x32_bf16 v[12:15], v[202:205], v[124:127], v[12:15]
	v_mfma_f32_16x16x32_bf16 v[20:23], v[194:197], v[178:181], v[20:23]
	v_mfma_f32_16x16x32_bf16 v[4:7], v[202:205], v[178:181], v[4:7]
	v_mfma_f32_16x16x32_bf16 v[32:35], v[194:197], v[186:189], v[32:35]
	v_mfma_f32_16x16x32_bf16 v[0:3], v[202:205], v[186:189], v[0:3]
	v_mfma_f32_16x16x32_bf16 v[48:51], v[194:197], v[116:119], v[48:51]
	s_add_i32 s63, 0, 0x18000
	v_add_u32_e32 v64, s63, v232
	s_barrier
	ds_read_b128 v[52:55], v64
	ds_read_b128 v[56:59], v64 offset:1024
	ds_read_b128 v[84:87], v64 offset:2048
	ds_read_b128 v[174:177], v64 offset:3072
	s_add_u32 s60, s90, 0x40000
	s_addc_u32 s61, s91, 0
	s_mov_b32 m0, s14
	v_lshl_add_u64 v[120:121], s[60:61], 0, v[160:161]
	ds_read_b128 v[64:67], v237 offset:32768
	ds_read_b128 v[112:115], v237 offset:33792
	ds_read_b128 v[116:119], v237 offset:34816
	ds_read_b128 v[178:181], v237 offset:35840
	ds_read_b128 v[182:185], v237 offset:36864
	ds_read_b128 v[186:189], v237 offset:37888
	ds_read_b128 v[190:193], v237 offset:38912
	ds_read_b128 v[194:197], v237 offset:39936
	global_load_lds_dwordx4 v[120:121], off
	v_lshl_add_u64 v[120:121], s[60:61], 0, v[162:163]
	s_mov_b32 m0, s15
	s_nop 0
	global_load_lds_dwordx4 v[120:121], off
	s_waitcnt lgkmcnt(8)
	s_waitcnt vmcnt(10)
	s_barrier
	s_waitcnt lgkmcnt(0)
	s_waitcnt lgkmcnt(0)
	v_mfma_f32_16x16x32_bf16 v[120:123], v[52:55], v[64:67], v[156:159]
	v_mfma_f32_16x16x32_bf16 v[156:159], v[56:59], v[112:115], v[120:123]
	v_mfma_f32_16x16x32_bf16 v[120:123], v[84:87], v[64:67], v[132:135]
	v_mfma_f32_16x16x32_bf16 v[132:135], v[174:177], v[112:115], v[120:123]
	v_mfma_f32_16x16x32_bf16 v[120:123], v[52:55], v[116:119], v[152:155]
	v_mfma_f32_16x16x32_bf16 v[152:155], v[56:59], v[178:181], v[120:123]
	v_mfma_f32_16x16x32_bf16 v[120:123], v[84:87], v[116:119], v[128:131]
	v_mfma_f32_16x16x32_bf16 v[128:131], v[174:177], v[178:181], v[120:123]
	v_mfma_f32_16x16x32_bf16 v[120:123], v[52:55], v[182:185], v[140:143]
	v_mfma_f32_16x16x32_bf16 v[140:143], v[56:59], v[186:189], v[120:123]
	v_mfma_f32_16x16x32_bf16 v[104:107], v[84:87], v[182:185], v[104:107]
	v_mfma_f32_16x16x32_bf16 v[120:123], v[52:55], v[190:193], v[144:147]
	v_mfma_f32_16x16x32_bf16 v[108:111], v[84:87], v[190:193], v[108:111]
	v_mfma_f32_16x16x32_bf16 v[104:107], v[174:177], v[186:189], v[104:107]
	v_mfma_f32_16x16x32_bf16 v[144:147], v[56:59], v[194:197], v[120:123]
	v_mfma_f32_16x16x32_bf16 v[108:111], v[174:177], v[194:197], v[108:111]
	s_barrier
	s_add_i32 s60, 0, 0x1c000
	s_nop 0
	v_add_u32_e32 v120, s60, v232
	s_add_i32 s61, s63, s11
	ds_read_b128 v[198:201], v120
	ds_read_b128 v[202:205], v120 offset:1024
	ds_read_b128 v[206:209], v120 offset:2048
	ds_read_b128 v[210:213], v120 offset:3072
	v_lshl_add_u64 v[120:121], v[214:215], 0, s[52:53]
	s_mov_b32 m0, s61
	s_nop 0
	global_load_lds_dwordx4 v[120:121], off
	v_lshl_add_u64 v[120:121], v[216:217], 0, s[52:53]
	s_add_i32 m0, s61, 0x2000
	s_nop 0
	global_load_lds_dwordx4 v[120:121], off
	s_waitcnt vmcnt(10)
	s_barrier
	s_waitcnt lgkmcnt(0)
	s_waitcnt lgkmcnt(0)
	v_mfma_f32_16x16x32_bf16 v[120:123], v[198:201], v[64:67], v[148:151]
	v_mfma_f32_16x16x32_bf16 v[64:67], v[206:209], v[64:67], v[68:71]
	v_mfma_f32_16x16x32_bf16 v[124:127], v[210:213], v[112:115], v[64:67]
	v_mfma_f32_16x16x32_bf16 v[64:67], v[198:201], v[116:119], v[72:75]
	v_mfma_f32_16x16x32_bf16 v[148:151], v[202:205], v[112:115], v[120:123]
	v_mfma_f32_16x16x32_bf16 v[120:123], v[202:205], v[178:181], v[64:67]
	v_mfma_f32_16x16x32_bf16 v[64:67], v[206:209], v[116:119], v[76:79]
	v_mfma_f32_16x16x32_bf16 v[112:115], v[210:213], v[178:181], v[64:67]
	v_mfma_f32_16x16x32_bf16 v[64:67], v[198:201], v[182:185], v[80:83]
	v_mfma_f32_16x16x32_bf16 v[116:119], v[202:205], v[186:189], v[64:67]
	v_mfma_f32_16x16x32_bf16 v[64:67], v[206:209], v[182:185], v[100:103]
	v_mfma_f32_16x16x32_bf16 v[100:103], v[210:213], v[186:189], v[64:67]
	v_mfma_f32_16x16x32_bf16 v[64:67], v[198:201], v[190:193], v[136:139]
	v_mfma_f32_16x16x32_bf16 v[136:139], v[202:205], v[194:197], v[64:67]
	v_mfma_f32_16x16x32_bf16 v[64:67], v[206:209], v[190:193], v[96:99]
	v_mfma_f32_16x16x32_bf16 v[96:99], v[210:213], v[194:197], v[64:67]
	s_mov_b32 m0, s17
	s_nop 4
	v_lshl_add_u64 v[64:65], v[218:219], 0, s[52:53]
	s_barrier
	ds_read_b128 v[68:71], v237 offset:49152
	ds_read_b128 v[72:75], v237 offset:50176
	ds_read_b128 v[76:79], v237 offset:51200
	ds_read_b128 v[80:83], v237 offset:52224
	ds_read_b128 v[178:181], v237 offset:53248
	ds_read_b128 v[182:185], v237 offset:54272
	ds_read_b128 v[186:189], v237 offset:55296
	ds_read_b128 v[190:193], v237 offset:56320
	global_load_lds_dwordx4 v[64:65], off
	v_lshl_add_u64 v[64:65], v[220:221], 0, s[52:53]
	s_mov_b32 m0, s18
	s_nop 0
	global_load_lds_dwordx4 v[64:65], off
	s_barrier
	s_waitcnt lgkmcnt(0)
	s_waitcnt lgkmcnt(0)
	v_mfma_f32_16x16x32_bf16 v[64:67], v[52:55], v[68:71], v[92:95]
	v_mfma_f32_16x16x32_bf16 v[92:95], v[56:59], v[72:75], v[64:67]
	v_mfma_f32_16x16x32_bf16 v[40:43], v[84:87], v[68:71], v[40:43]
	v_mfma_f32_16x16x32_bf16 v[64:67], v[52:55], v[76:79], v[88:91]
	v_mfma_f32_16x16x32_bf16 v[36:39], v[84:87], v[76:79], v[36:39]
	v_mfma_f32_16x16x32_bf16 v[60:63], v[52:55], v[178:181], v[60:63]
	v_mfma_f32_16x16x32_bf16 v[8:11], v[84:87], v[178:181], v[8:11]
	v_mfma_f32_16x16x32_bf16 v[44:47], v[52:55], v[186:189], v[44:47]
	v_mfma_f32_16x16x32_bf16 v[16:19], v[84:87], v[186:189], v[16:19]
	v_mfma_f32_16x16x32_bf16 v[40:43], v[174:177], v[72:75], v[40:43]
	v_mfma_f32_16x16x32_bf16 v[88:91], v[56:59], v[80:83], v[64:67]
	v_mfma_f32_16x16x32_bf16 v[36:39], v[174:177], v[80:83], v[36:39]
	v_mfma_f32_16x16x32_bf16 v[60:63], v[56:59], v[182:185], v[60:63]
	v_mfma_f32_16x16x32_bf16 v[8:11], v[174:177], v[182:185], v[8:11]
	v_mfma_f32_16x16x32_bf16 v[64:67], v[56:59], v[190:193], v[44:47]
	v_mfma_f32_16x16x32_bf16 v[16:19], v[174:177], v[190:193], v[16:19]
	s_barrier
	s_add_u32 s0, s0, 0x40080
	s_addc_u32 s1, s1, 0
	s_add_i32 s60, s60, s11
	v_lshl_add_u64 v[44:45], s[0:1], 0, v[160:161]
	s_mov_b32 m0, s60
	s_nop 0
	global_load_lds_dwordx4 v[44:45], off
	v_lshl_add_u64 v[44:45], s[0:1], 0, v[162:163]
	s_add_i32 m0, s60, 0x2000
	s_nop 0
	global_load_lds_dwordx4 v[44:45], off
	s_waitcnt vmcnt(10)
	s_barrier
	v_mfma_f32_16x16x32_bf16 v[44:47], v[198:201], v[68:71], v[48:51]
	v_mfma_f32_16x16x32_bf16 v[28:31], v[206:209], v[68:71], v[28:31]
	v_mfma_f32_16x16x32_bf16 v[24:27], v[198:201], v[76:79], v[24:27]
	v_mfma_f32_16x16x32_bf16 v[12:15], v[206:209], v[76:79], v[12:15]
	v_mfma_f32_16x16x32_bf16 v[20:23], v[198:201], v[178:181], v[20:23]
	v_mfma_f32_16x16x32_bf16 v[4:7], v[206:209], v[178:181], v[4:7]
	v_mfma_f32_16x16x32_bf16 v[32:35], v[198:201], v[186:189], v[32:35]
	v_mfma_f32_16x16x32_bf16 v[0:3], v[206:209], v[186:189], v[0:3]
	v_mfma_f32_16x16x32_bf16 v[84:87], v[202:205], v[72:75], v[44:47]
	v_mfma_f32_16x16x32_bf16 v[28:31], v[210:213], v[72:75], v[28:31]
	v_mfma_f32_16x16x32_bf16 v[24:27], v[202:205], v[80:83], v[24:27]
	v_mfma_f32_16x16x32_bf16 v[12:15], v[210:213], v[80:83], v[12:15]
	v_mfma_f32_16x16x32_bf16 v[20:23], v[202:205], v[182:185], v[20:23]
	v_mfma_f32_16x16x32_bf16 v[4:7], v[210:213], v[182:185], v[4:7]
	v_mfma_f32_16x16x32_bf16 v[32:35], v[202:205], v[190:193], v[32:35]
	v_mfma_f32_16x16x32_bf16 v[0:3], v[210:213], v[190:193], v[0:3]
	s_add_i32 s59, s59, 2
	s_add_u32 vcc_lo, vcc_lo, 0x100
	s_addc_u32 vcc_hi, vcc_hi, 0
	s_add_u32 s55, s55, 0x100
	s_addc_u32 s57, s57, 0
	s_cmp_gt_u32 s59, 13
	s_barrier
	s_cbranch_scc0 .LBB0_703
	v_lshl_add_u32 v164, s84, 8, v231
	v_lshl_add_u64 v[44:45], v[164:165], 2, s[34:35]
	global_load_dword v184, v[44:45], off
	v_or_b32_e32 v182, 16, v164
	v_mov_b32_e32 v183, v165
	v_lshl_add_u64 v[44:45], v[182:183], 2, s[34:35]
	global_load_dword v186, v[44:45], off
	v_or_b32_e32 v44, 32, v164
	v_mov_b32_e32 v45, v165
	v_lshl_add_u64 v[44:45], v[44:45], 2, s[34:35]
	v_or_b32_e32 v180, 48, v164
	v_mov_b32_e32 v181, v165
	global_load_dword v200, v[44:45], off
	v_lshl_add_u64 v[44:45], v[180:181], 2, s[34:35]
	v_add_u32_e32 v178, 0x80, v164
	v_mov_b32_e32 v179, v165
	global_load_dword v185, v[44:45], off
	v_lshl_add_u64 v[44:45], v[178:179], 2, s[34:35]
	v_add_u32_e32 v174, 0x90, v164
	v_mov_b32_e32 v175, v165
	global_load_dword v183, v[44:45], off
	v_lshl_add_u64 v[44:45], v[174:175], 2, s[34:35]
	global_load_dword v181, v[44:45], off
	v_add_u32_e32 v44, 0xa0, v164
	v_mov_b32_e32 v45, v165
	v_lshl_add_u64 v[44:45], v[44:45], 2, s[34:35]
	global_load_dword v175, v[44:45], off
	v_add_u32_e32 v44, 0xb0, v164
	v_mov_b32_e32 v45, v165
	v_lshl_or_b32 v176, s88, 7, v235
	v_lshl_add_u64 v[44:45], v[44:45], 2, s[34:35]
	v_ashrrev_i32_e32 v177, 31, v176
	v_readlane_b32 s44, v254, 1
	global_load_dword v179, v[44:45], off
	v_lshlrev_b64 v[44:45], 2, v[176:177]
	v_readlane_b32 s48, v254, 5
	v_readlane_b32 s49, v254, 6
	v_readlane_b32 s50, v254, 7
	v_readlane_b32 s51, v254, 8
	v_lshl_add_u64 v[48:49], s[48:49], 0, v[44:45]
	v_lshl_add_u64 v[52:53], s[96:97], 0, v[44:45]
	v_lshl_add_u64 v[56:57], s[86:87], 0, v[44:45]
	v_lshl_add_u64 v[80:81], s[50:51], 0, v[44:45]
	global_load_dwordx4 v[44:47], v[48:49], off offset:16
	global_load_dwordx4 v[68:71], v[48:49], off
	s_nop 0
	global_load_dwordx4 v[48:51], v[52:53], off offset:16
	global_load_dwordx4 v[72:75], v[52:53], off
	s_nop 0
	global_load_dwordx4 v[52:55], v[56:57], off offset:16
	global_load_dwordx4 v[76:79], v[56:57], off
	s_nop 0
	global_load_dwordx4 v[56:59], v[80:81], off offset:16
	s_nop 0
	global_load_dwordx4 v[80:83], v[80:81], off
	v_mov_b32_e32 v190, 0
	v_mov_b32_e32 v192, 0
	v_mov_b32_e32 v191, 0
	v_mov_b32_e32 v193, 0
	v_mov_b32_e32 v196, 0
	s_lshl_b32 s3, s84, 2
	v_mov_b32_e32 v198, 0
	s_add_i32 s3, s3, s10
	v_mov_b32_e32 v197, 0
	s_mul_i32 s51, s3, 6
	v_mov_b32_e32 v199, 0
	v_readlane_b32 s45, v254, 2
	v_readlane_b32 s46, v254, 3
	v_readlane_b32 s47, v254, 4
	s_waitcnt vmcnt(0)
	v_fmamk_f32 v177, v184, 0x3a800000, v239
	v_cmp_gt_f32_e32 vcc, s33, v177
	v_mul_f32_e32 v184, 0x4b800000, v177
	s_nop 0
	v_cndmask_b32_e32 v177, v177, v184, vcc
	v_rsq_f32_e32 v177, v177
	s_nop 0
	v_mul_f32_e32 v184, 0x45800000, v177
	v_cndmask_b32_e32 v188, v177, v184, vcc
	v_fmamk_f32 v177, v186, 0x3a800000, v239
	v_cmp_gt_f32_e32 vcc, s33, v177
	v_mul_f32_e32 v184, 0x4b800000, v177
	v_pk_mul_f32 v[186:187], v[156:157], v[188:189] op_sel_hi:[1,0]
	v_cndmask_b32_e32 v177, v177, v184, vcc
	v_rsq_f32_e32 v177, v177
	v_cndmask_b32_e64 v156, v186, 0, s[38:39]
	v_pk_mul_f32 v[194:195], v[158:159], v[188:189] op_sel_hi:[1,0]
	v_mul_f32_e32 v184, 0x45800000, v177
	v_cndmask_b32_e32 v184, v177, v184, vcc
	v_mov_b32_dpp v190, v156 row_ror:1 row_mask:0xf bank_mask:0xf
	v_pk_mul_f32 v[156:157], v[152:153], v[184:185] op_sel_hi:[1,0]
	v_pk_mul_f32 v[158:159], v[154:155], v[184:185] op_sel_hi:[1,0]
	v_cndmask_b32_e64 v152, v186, v156, s[42:43]
	v_add_u32_e32 v155, s51, v234
	s_nop 0
	v_mov_b32_dpp v192, v152 row_ror:15 row_mask:0xf bank_mask:0xf
	v_cndmask_b32_e64 v152, v187, 0, s[38:39]
	s_nop 1
	v_mov_b32_dpp v191, v152 row_ror:1 row_mask:0xf bank_mask:0xf
	v_cndmask_b32_e64 v152, v187, v157, s[42:43]
	s_nop 1
	v_mov_b32_dpp v193, v152 row_ror:15 row_mask:0xf bank_mask:0xf
	v_cndmask_b32_e64 v152, v194, 0, s[38:39]
	s_nop 1
	v_mov_b32_dpp v196, v152 row_ror:1 row_mask:0xf bank_mask:0xf
	v_cndmask_b32_e64 v152, v194, v158, s[42:43]
	s_nop 1
	v_mov_b32_dpp v198, v152 row_ror:15 row_mask:0xf bank_mask:0xf
	v_cndmask_b32_e64 v152, v195, 0, s[38:39]
	s_nop 1
	v_mov_b32_dpp v197, v152 row_ror:1 row_mask:0xf bank_mask:0xf
	v_cndmask_b32_e64 v152, v195, v159, s[42:43]
	s_nop 1
	v_mov_b32_dpp v199, v152 row_ror:15 row_mask:0xf bank_mask:0xf
	s_and_saveexec_b64 s[0:1], s[70:71]
	s_cbranch_execz .LBB0_706
	v_mad_u64_u32 v[202:203], s[22:23], v155, s65, v[176:177]
	v_mov_b32_e32 v203, v165
	v_cvt_pk_bf16_f32 v152, v186, v187
	v_cvt_pk_bf16_f32 v153, v194, v195
	v_lshl_add_u64 v[202:203], v[202:203], 1, s[30:31]
	global_store_dwordx2 v[202:203], v[152:153], off

.LBB0_868:
	s_cmp_lt_i32 s82, 14
	s_cselect_b64 s[0:1], -1, 0
	s_and_b64 s[0:1], s[0:1], s[2:3]
	s_andn2_b64 vcc, exec, s[0:1]
	s_cbranch_vccnz .LBB0_893
	s_mov_b64 s[0:1], 0
	v_readlane_b32 s2, v254, 0
	v_mov_b32_e32 v0, v230
	s_cmpk_gt_i32 s2, 0x3ff
	v_readfirstlane_b32 s16, v230
	s_cbranch_scc1 .LBB0_893
	s_mov_b32 s41, s2
	s_ashr_i32 s17, s41, 31
	s_lshr_b32 s2, s17, 29
	s_add_i32 s4, s41, s2
	s_and_b32 s2, s4, -8
	s_sub_i32 s6, s41, s2
	s_cmp_gt_i32 s6, -1
	s_cbranch_scc0 .LBB0_872
	s_lshl_b32 s7, s6, 7
	s_ashr_i32 s2, s4, 3
	s_cbranch_execz .LBB0_873
	s_branch .LBB0_874
	s_nop 0
	s_nop 0
	s_nop 0
	s_nop 0
	s_nop 0
	s_nop 0
	s_nop 0
	s_nop 0
	s_nop 0
	s_nop 0
	s_nop 0
	s_nop 0

.LBB0_888:
	ds_read_b128 v[140:143], v149
	ds_read_b128 v[152:155], v149 offset:1024
	ds_read_b128 v[156:159], v149 offset:2048
	ds_read_b128 v[160:163], v149 offset:3072
	s_add_u32 s10, s2, 0x100
	s_addc_u32 s11, s3, 0
	s_cmp_eq_u32 s39, 40
	s_cselect_b32 s15, s7, s11
	s_cselect_b32 s14, s6, s10
	s_cselect_b32 s13, s5, s38
	s_cselect_b32 s12, s4, s37
	v_lshl_add_u64 v[144:145], s[2:3], 0, v[132:133]
	s_add_i32 m0, s23, 0xc000
	ds_read_b128 v[164:167], v150
	ds_read_b128 v[168:171], v150 offset:1024
	ds_read_b128 v[172:175], v150 offset:2048
	ds_read_b128 v[176:179], v150 offset:3072
	ds_read_b128 v[180:183], v150 offset:4096
	ds_read_b128 v[184:187], v150 offset:5120
	ds_read_b128 v[188:191], v150 offset:6144
	ds_read_b128 v[192:195], v150 offset:7168
	global_load_lds_dwordx4 v[144:145], off
	v_lshl_add_u64 v[144:145], s[2:3], 0, v[134:135]
	s_add_i32 m0, s23, 0xe000
	s_nop 0
	global_load_lds_dwordx4 v[144:145], off
	s_waitcnt lgkmcnt(8)
	s_waitcnt vmcnt(10)
	s_barrier
	s_waitcnt lgkmcnt(0)
	s_waitcnt lgkmcnt(0)
	v_mfma_f32_16x16x32_bf16 v[124:127], v[140:143], v[164:167], v[124:127]
	v_mfma_f32_16x16x32_bf16 v[120:123], v[156:159], v[164:167], v[120:123]
	v_mfma_f32_16x16x32_bf16 v[116:119], v[140:143], v[172:175], v[116:119]
	v_mfma_f32_16x16x32_bf16 v[112:115], v[156:159], v[172:175], v[112:115]
	v_mfma_f32_16x16x32_bf16 v[92:95], v[140:143], v[180:183], v[92:95]
	v_mfma_f32_16x16x32_bf16 v[88:91], v[156:159], v[180:183], v[88:91]
	v_mfma_f32_16x16x32_bf16 v[84:87], v[140:143], v[188:191], v[84:87]
	v_mfma_f32_16x16x32_bf16 v[80:83], v[156:159], v[188:191], v[80:83]
	v_mfma_f32_16x16x32_bf16 v[124:127], v[152:155], v[168:171], v[124:127]
	v_mfma_f32_16x16x32_bf16 v[120:123], v[160:163], v[168:171], v[120:123]
	v_mfma_f32_16x16x32_bf16 v[116:119], v[152:155], v[176:179], v[116:119]
	v_mfma_f32_16x16x32_bf16 v[112:115], v[160:163], v[176:179], v[112:115]
	v_mfma_f32_16x16x32_bf16 v[92:95], v[152:155], v[184:187], v[92:95]
	v_mfma_f32_16x16x32_bf16 v[88:91], v[160:163], v[184:187], v[88:91]
	v_mfma_f32_16x16x32_bf16 v[84:87], v[152:155], v[192:195], v[84:87]
	v_mfma_f32_16x16x32_bf16 v[80:83], v[160:163], v[192:195], v[80:83]
	s_barrier
	s_add_i32 s2, s30, s22
	v_lshl_add_u64 v[144:145], s[12:13], 0, v[128:129]
	s_mov_b32 m0, s2
	ds_read_b128 v[196:199], v151
	ds_read_b128 v[200:203], v151 offset:1024
	ds_read_b128 v[204:207], v151 offset:2048
	ds_read_b128 v[208:211], v151 offset:3072
	global_load_lds_dwordx4 v[144:145], off
	v_lshl_add_u64 v[212:213], s[12:13], 0, v[130:131]
	s_add_i32 m0, s2, 0x2000
	s_nop 0
	global_load_lds_dwordx4 v[212:213], off
	s_waitcnt vmcnt(10)
	s_barrier
	s_waitcnt lgkmcnt(0)
	s_waitcnt lgkmcnt(0)
	v_mfma_f32_16x16x32_bf16 v[108:111], v[196:199], v[164:167], v[108:111]
	v_mfma_f32_16x16x32_bf16 v[104:107], v[204:207], v[164:167], v[104:107]
	v_mfma_f32_16x16x32_bf16 v[100:103], v[196:199], v[172:175], v[100:103]
	v_mfma_f32_16x16x32_bf16 v[96:99], v[204:207], v[172:175], v[96:99]
	v_mfma_f32_16x16x32_bf16 v[76:79], v[196:199], v[180:183], v[76:79]
	v_mfma_f32_16x16x32_bf16 v[72:75], v[204:207], v[180:183], v[72:75]
	v_mfma_f32_16x16x32_bf16 v[68:71], v[196:199], v[188:191], v[68:71]
	v_mfma_f32_16x16x32_bf16 v[64:67], v[204:207], v[188:191], v[64:67]
	v_mfma_f32_16x16x32_bf16 v[108:111], v[200:203], v[168:171], v[108:111]
	v_mfma_f32_16x16x32_bf16 v[104:107], v[208:211], v[168:171], v[104:107]
	v_mfma_f32_16x16x32_bf16 v[100:103], v[200:203], v[176:179], v[100:103]
	v_mfma_f32_16x16x32_bf16 v[96:99], v[208:211], v[176:179], v[96:99]
	v_mfma_f32_16x16x32_bf16 v[76:79], v[200:203], v[184:187], v[76:79]
	v_mfma_f32_16x16x32_bf16 v[72:75], v[208:211], v[184:187], v[72:75]
	v_mfma_f32_16x16x32_bf16 v[68:71], v[200:203], v[192:195], v[68:71]
	v_mfma_f32_16x16x32_bf16 v[64:67], v[208:211], v[192:195], v[64:67]
	s_mov_b32 m0, s23
	v_lshl_add_u64 v[214:215], s[14:15], 0, v[128:129]
	s_barrier
	ds_read_b128 v[164:167], v150 offset:16384
	ds_read_b128 v[168:171], v150 offset:17408
	ds_read_b128 v[172:175], v150 offset:18432
	ds_read_b128 v[176:179], v150 offset:19456
	ds_read_b128 v[180:183], v150 offset:20480
	ds_read_b128 v[184:187], v150 offset:21504
	ds_read_b128 v[188:191], v150 offset:22528
	ds_read_b128 v[192:195], v150 offset:23552
	global_load_lds_dwordx4 v[214:215], off
	v_lshl_add_u64 v[216:217], s[14:15], 0, v[130:131]
	s_mov_b32 m0, s24
	s_nop 0
	global_load_lds_dwordx4 v[216:217], off
	s_barrier
	s_waitcnt lgkmcnt(0)
	s_waitcnt lgkmcnt(0)
	v_mfma_f32_16x16x32_bf16 v[60:63], v[140:143], v[164:167], v[60:63]
	v_mfma_f32_16x16x32_bf16 v[56:59], v[156:159], v[164:167], v[56:59]
	v_mfma_f32_16x16x32_bf16 v[52:55], v[140:143], v[172:175], v[52:55]
	v_mfma_f32_16x16x32_bf16 v[48:51], v[156:159], v[172:175], v[48:51]
	v_mfma_f32_16x16x32_bf16 v[28:31], v[140:143], v[180:183], v[28:31]
	v_mfma_f32_16x16x32_bf16 v[24:27], v[156:159], v[180:183], v[24:27]
	v_mfma_f32_16x16x32_bf16 v[16:19], v[140:143], v[188:191], v[16:19]
	v_mfma_f32_16x16x32_bf16 v[8:11], v[156:159], v[188:191], v[8:11]
	v_mfma_f32_16x16x32_bf16 v[60:63], v[152:155], v[168:171], v[60:63]
	v_mfma_f32_16x16x32_bf16 v[56:59], v[160:163], v[168:171], v[56:59]
	v_mfma_f32_16x16x32_bf16 v[52:55], v[152:155], v[176:179], v[52:55]
	v_mfma_f32_16x16x32_bf16 v[48:51], v[160:163], v[176:179], v[48:51]
	v_mfma_f32_16x16x32_bf16 v[28:31], v[152:155], v[184:187], v[28:31]
	v_mfma_f32_16x16x32_bf16 v[24:27], v[160:163], v[184:187], v[24:27]
	v_mfma_f32_16x16x32_bf16 v[16:19], v[152:155], v[192:195], v[16:19]
	v_mfma_f32_16x16x32_bf16 v[8:11], v[160:163], v[192:195], v[8:11]
	s_barrier
	s_add_u32 s2, s12, 0xb0000
	s_addc_u32 s3, s13, 0
	s_add_i32 s40, s31, s22
	v_lshl_add_u64 v[140:141], s[2:3], 0, v[128:129]
	s_mov_b32 m0, s40
	s_nop 0
	global_load_lds_dwordx4 v[140:141], off
	v_lshl_add_u64 v[140:141], s[2:3], 0, v[130:131]
	s_add_i32 m0, s40, 0x2000
	s_nop 0
	global_load_lds_dwordx4 v[140:141], off
	s_waitcnt vmcnt(10)
	s_barrier
	v_mfma_f32_16x16x32_bf16 v[44:47], v[196:199], v[164:167], v[44:47]
	v_mfma_f32_16x16x32_bf16 v[40:43], v[204:207], v[164:167], v[40:43]
	v_mfma_f32_16x16x32_bf16 v[36:39], v[196:199], v[172:175], v[36:39]
	v_mfma_f32_16x16x32_bf16 v[32:35], v[204:207], v[172:175], v[32:35]
	v_mfma_f32_16x16x32_bf16 v[20:23], v[196:199], v[180:183], v[20:23]
	v_mfma_f32_16x16x32_bf16 v[12:15], v[204:207], v[180:183], v[12:15]
	v_mfma_f32_16x16x32_bf16 v[4:7], v[196:199], v[188:191], v[4:7]
	v_mfma_f32_16x16x32_bf16 v[0:3], v[204:207], v[188:191], v[0:3]
	v_mfma_f32_16x16x32_bf16 v[44:47], v[200:203], v[168:171], v[44:47]
	v_mfma_f32_16x16x32_bf16 v[40:43], v[208:211], v[168:171], v[40:43]
	v_mfma_f32_16x16x32_bf16 v[36:39], v[200:203], v[176:179], v[36:39]
	v_mfma_f32_16x16x32_bf16 v[32:35], v[208:211], v[176:179], v[32:35]
	v_mfma_f32_16x16x32_bf16 v[20:23], v[200:203], v[184:187], v[20:23]
	v_mfma_f32_16x16x32_bf16 v[12:15], v[208:211], v[184:187], v[12:15]
	v_mfma_f32_16x16x32_bf16 v[4:7], v[200:203], v[192:195], v[4:7]
	v_mfma_f32_16x16x32_bf16 v[0:3], v[208:211], v[192:195], v[0:3]
	s_add_i32 s40, 0, 0x18000
	v_add_u32_e32 v160, s40, v147
	s_barrier
	ds_read_b128 v[140:143], v160
	ds_read_b128 v[152:155], v160 offset:1024
	ds_read_b128 v[156:159], v160 offset:2048
	ds_read_b128 v[160:163], v160 offset:3072
	s_add_u32 s2, s14, 0xb0000
	s_addc_u32 s3, s15, 0
	s_mov_b32 m0, s25
	v_lshl_add_u64 v[196:197], s[2:3], 0, v[128:129]
	ds_read_b128 v[164:167], v150 offset:32768
	ds_read_b128 v[168:171], v150 offset:33792
	ds_read_b128 v[172:175], v150 offset:34816
	ds_read_b128 v[176:179], v150 offset:35840
	ds_read_b128 v[180:183], v150 offset:36864
	ds_read_b128 v[184:187], v150 offset:37888
	ds_read_b128 v[188:191], v150 offset:38912
	ds_read_b128 v[192:195], v150 offset:39936
	global_load_lds_dwordx4 v[196:197], off
	v_lshl_add_u64 v[196:197], s[2:3], 0, v[130:131]
	s_mov_b32 m0, s26
	s_nop 0
	global_load_lds_dwordx4 v[196:197], off
	s_waitcnt lgkmcnt(8)
	s_waitcnt vmcnt(10)
	s_barrier
	s_waitcnt lgkmcnt(0)
	s_waitcnt lgkmcnt(0)
	v_mfma_f32_16x16x32_bf16 v[124:127], v[140:143], v[164:167], v[124:127]
	v_mfma_f32_16x16x32_bf16 v[120:123], v[156:159], v[164:167], v[120:123]
	v_mfma_f32_16x16x32_bf16 v[116:119], v[140:143], v[172:175], v[116:119]
	v_mfma_f32_16x16x32_bf16 v[112:115], v[156:159], v[172:175], v[112:115]
	v_mfma_f32_16x16x32_bf16 v[92:95], v[140:143], v[180:183], v[92:95]
	v_mfma_f32_16x16x32_bf16 v[88:91], v[156:159], v[180:183], v[88:91]
	v_mfma_f32_16x16x32_bf16 v[84:87], v[140:143], v[188:191], v[84:87]
	v_mfma_f32_16x16x32_bf16 v[80:83], v[156:159], v[188:191], v[80:83]
	v_mfma_f32_16x16x32_bf16 v[124:127], v[152:155], v[168:171], v[124:127]
	v_mfma_f32_16x16x32_bf16 v[120:123], v[160:163], v[168:171], v[120:123]
	v_mfma_f32_16x16x32_bf16 v[116:119], v[152:155], v[176:179], v[116:119]
	v_mfma_f32_16x16x32_bf16 v[112:115], v[160:163], v[176:179], v[112:115]
	v_mfma_f32_16x16x32_bf16 v[92:95], v[152:155], v[184:187], v[92:95]
	v_mfma_f32_16x16x32_bf16 v[88:91], v[160:163], v[184:187], v[88:91]
	v_mfma_f32_16x16x32_bf16 v[84:87], v[152:155], v[192:195], v[84:87]
	v_mfma_f32_16x16x32_bf16 v[80:83], v[160:163], v[192:195], v[80:83]
	s_barrier
	s_add_i32 s14, 0, 0x1c000
	s_add_i32 s2, s40, s22
	v_add_u32_e32 v208, s14, v147
	v_lshl_add_u64 v[144:145], v[144:145], 0, s[8:9]
	s_mov_b32 m0, s2
	ds_read_b128 v[196:199], v208
	ds_read_b128 v[200:203], v208 offset:1024
	ds_read_b128 v[204:207], v208 offset:2048
	ds_read_b128 v[208:211], v208 offset:3072
	global_load_lds_dwordx4 v[144:145], off
	v_lshl_add_u64 v[144:145], v[212:213], 0, s[8:9]
	s_add_i32 m0, s2, 0x2000
	s_nop 0
	global_load_lds_dwordx4 v[144:145], off
	s_waitcnt vmcnt(10)
	s_barrier
	s_waitcnt lgkmcnt(0)
	s_waitcnt lgkmcnt(0)
	v_mfma_f32_16x16x32_bf16 v[108:111], v[196:199], v[164:167], v[108:111]
	v_mfma_f32_16x16x32_bf16 v[104:107], v[204:207], v[164:167], v[104:107]
	v_mfma_f32_16x16x32_bf16 v[100:103], v[196:199], v[172:175], v[100:103]
	v_mfma_f32_16x16x32_bf16 v[96:99], v[204:207], v[172:175], v[96:99]
	v_mfma_f32_16x16x32_bf16 v[76:79], v[196:199], v[180:183], v[76:79]
	v_mfma_f32_16x16x32_bf16 v[72:75], v[204:207], v[180:183], v[72:75]
	v_mfma_f32_16x16x32_bf16 v[68:71], v[196:199], v[188:191], v[68:71]
	v_mfma_f32_16x16x32_bf16 v[64:67], v[204:207], v[188:191], v[64:67]
	v_mfma_f32_16x16x32_bf16 v[108:111], v[200:203], v[168:171], v[108:111]
	v_mfma_f32_16x16x32_bf16 v[104:107], v[208:211], v[168:171], v[104:107]
	v_mfma_f32_16x16x32_bf16 v[100:103], v[200:203], v[176:179], v[100:103]
	v_mfma_f32_16x16x32_bf16 v[96:99], v[208:211], v[176:179], v[96:99]
	v_mfma_f32_16x16x32_bf16 v[76:79], v[200:203], v[184:187], v[76:79]
	v_mfma_f32_16x16x32_bf16 v[72:75], v[208:211], v[184:187], v[72:75]
	v_mfma_f32_16x16x32_bf16 v[68:71], v[200:203], v[192:195], v[68:71]
	v_mfma_f32_16x16x32_bf16 v[64:67], v[208:211], v[192:195], v[64:67]
	s_mov_b32 m0, s28
	v_lshl_add_u64 v[144:145], v[214:215], 0, s[8:9]
	s_barrier
	ds_read_b128 v[164:167], v150 offset:49152
	ds_read_b128 v[168:171], v150 offset:50176
	ds_read_b128 v[172:175], v150 offset:51200
	ds_read_b128 v[176:179], v150 offset:52224
	ds_read_b128 v[180:183], v150 offset:53248
	ds_read_b128 v[184:187], v150 offset:54272
	ds_read_b128 v[188:191], v150 offset:55296
	ds_read_b128 v[192:195], v150 offset:56320
	global_load_lds_dwordx4 v[144:145], off
	v_lshl_add_u64 v[144:145], v[216:217], 0, s[8:9]
	s_mov_b32 m0, s29
	s_nop 0
	global_load_lds_dwordx4 v[144:145], off
	s_barrier
	s_waitcnt lgkmcnt(0)
	s_waitcnt lgkmcnt(0)
	v_mfma_f32_16x16x32_bf16 v[60:63], v[140:143], v[164:167], v[60:63]
	v_mfma_f32_16x16x32_bf16 v[56:59], v[156:159], v[164:167], v[56:59]
	v_mfma_f32_16x16x32_bf16 v[52:55], v[140:143], v[172:175], v[52:55]
	v_mfma_f32_16x16x32_bf16 v[48:51], v[156:159], v[172:175], v[48:51]
	v_mfma_f32_16x16x32_bf16 v[28:31], v[140:143], v[180:183], v[28:31]
	v_mfma_f32_16x16x32_bf16 v[24:27], v[156:159], v[180:183], v[24:27]
	v_mfma_f32_16x16x32_bf16 v[16:19], v[140:143], v[188:191], v[16:19]
	v_mfma_f32_16x16x32_bf16 v[8:11], v[156:159], v[188:191], v[8:11]
	v_mfma_f32_16x16x32_bf16 v[60:63], v[152:155], v[168:171], v[60:63]
	v_mfma_f32_16x16x32_bf16 v[56:59], v[160:163], v[168:171], v[56:59]
	v_mfma_f32_16x16x32_bf16 v[52:55], v[152:155], v[176:179], v[52:55]
	v_mfma_f32_16x16x32_bf16 v[48:51], v[160:163], v[176:179], v[48:51]
	v_mfma_f32_16x16x32_bf16 v[28:31], v[152:155], v[184:187], v[28:31]
	v_mfma_f32_16x16x32_bf16 v[24:27], v[160:163], v[184:187], v[24:27]
	v_mfma_f32_16x16x32_bf16 v[16:19], v[152:155], v[192:195], v[16:19]
	v_mfma_f32_16x16x32_bf16 v[8:11], v[160:163], v[192:195], v[8:11]
	s_barrier
	s_add_u32 s2, s12, 0xb0080
	s_addc_u32 s3, s13, 0
	s_add_i32 s12, s14, s22
	v_lshl_add_u64 v[140:141], s[2:3], 0, v[128:129]
	s_mov_b32 m0, s12
	s_nop 0
	global_load_lds_dwordx4 v[140:141], off
	v_lshl_add_u64 v[140:141], s[2:3], 0, v[130:131]
	s_add_i32 m0, s12, 0x2000
	s_nop 0
	global_load_lds_dwordx4 v[140:141], off
	s_waitcnt vmcnt(10)
	s_barrier
	v_mfma_f32_16x16x32_bf16 v[44:47], v[196:199], v[164:167], v[44:47]
	v_mfma_f32_16x16x32_bf16 v[40:43], v[204:207], v[164:167], v[40:43]
	v_mfma_f32_16x16x32_bf16 v[36:39], v[196:199], v[172:175], v[36:39]
	v_mfma_f32_16x16x32_bf16 v[32:35], v[204:207], v[172:175], v[32:35]
	v_mfma_f32_16x16x32_bf16 v[20:23], v[196:199], v[180:183], v[20:23]
	v_mfma_f32_16x16x32_bf16 v[12:15], v[204:207], v[180:183], v[12:15]
	v_mfma_f32_16x16x32_bf16 v[4:7], v[196:199], v[188:191], v[4:7]
	v_mfma_f32_16x16x32_bf16 v[0:3], v[204:207], v[188:191], v[0:3]
	v_mfma_f32_16x16x32_bf16 v[44:47], v[200:203], v[168:171], v[44:47]
	v_mfma_f32_16x16x32_bf16 v[40:43], v[208:211], v[168:171], v[40:43]
	v_mfma_f32_16x16x32_bf16 v[36:39], v[200:203], v[176:179], v[36:39]
	v_mfma_f32_16x16x32_bf16 v[32:35], v[208:211], v[176:179], v[32:35]
	v_mfma_f32_16x16x32_bf16 v[20:23], v[200:203], v[184:187], v[20:23]
	v_mfma_f32_16x16x32_bf16 v[12:15], v[208:211], v[184:187], v[12:15]
	v_mfma_f32_16x16x32_bf16 v[4:7], v[200:203], v[192:195], v[4:7]
	v_mfma_f32_16x16x32_bf16 v[0:3], v[208:211], v[192:195], v[0:3]
	s_add_i32 s39, s39, 2
	s_add_u32 s37, s37, 0x100
	s_addc_u32 s38, s38, 0
	s_cmp_gt_u32 s39, 41
	s_mov_b64 s[2:3], s[10:11]
	s_barrier
	s_cbranch_scc0 .LBB0_888
	v_lshl_or_b32 v140, s36, 8, v148
	v_lshl_add_u32 v144, s35, 8, v146
	v_ashrrev_i32_e32 v141, 31, v140
	v_lshlrev_b64 v[140:141], 2, v[140:141]
	v_ashrrev_i32_e32 v145, 31, v144
	v_lshl_add_u64 v[142:143], s[78:79], 0, v[140:141]
	v_lshlrev_b64 v[184:185], 12, v[144:145]
	v_lshl_add_u64 v[164:165], v[142:143], 0, v[184:185]
	v_or_b32_e32 v168, 16, v144
	global_load_dwordx4 v[152:155], v[164:165], off offset:16
	global_load_dwordx4 v[156:159], v[164:165], off
	global_load_dwordx4 v[160:163], v[164:165], off offset:144
	s_nop 0
	global_load_dwordx4 v[164:167], v[164:165], off offset:128
	v_ashrrev_i32_e32 v169, 31, v168
	v_lshlrev_b64 v[186:187], 12, v[168:169]
	v_lshl_add_u64 v[180:181], v[142:143], 0, v[186:187]
	global_load_dwordx4 v[168:171], v[180:181], off offset:16
	global_load_dwordx4 v[172:175], v[180:181], off
	global_load_dwordx4 v[176:179], v[180:181], off offset:144
	s_nop 0
	global_load_dwordx4 v[180:183], v[180:181], off offset:128
	s_and_b64 vcc, exec, s[0:1]
	s_mov_b32 s36, s34
	s_mov_b32 s35, s33
	s_mov_b64 s[10:11], s[4:5]
	s_mov_b64 s[2:3], s[6:7]
	s_waitcnt vmcnt(0)
	v_pk_add_f32 v[120:121], v[120:121], v[152:153]
	v_lshl_add_u64 v[152:153], s[78:79], 0, v[184:185]
	v_pk_add_f32 v[126:127], v[126:127], v[158:159]
	v_pk_add_f32 v[124:125], v[124:125], v[156:157]
	v_pk_add_f32 v[108:109], v[108:109], v[164:165]
	v_lshl_add_u64 v[152:153], v[152:153], 0, v[140:141]
	v_pk_add_f32 v[122:123], v[122:123], v[154:155]
	v_pk_add_f32 v[110:111], v[110:111], v[166:167]
	v_pk_add_f32 v[106:107], v[106:107], v[162:163]
	v_pk_add_f32 v[104:105], v[104:105], v[160:161]
	global_store_dwordx4 v[152:153], v[124:127], off nt
	global_store_dwordx4 v[152:153], v[120:123], off offset:16 nt
	global_store_dwordx4 v[152:153], v[108:111], off offset:128 nt
	global_store_dwordx4 v[152:153], v[104:107], off offset:144 nt
	v_pk_add_f32 v[96:97], v[96:97], v[176:177]
	v_pk_add_f32 v[108:109], v[112:113], v[168:169]
	v_lshl_add_u64 v[112:113], s[78:79], 0, v[186:187]
	v_pk_add_f32 v[106:107], v[118:119], v[174:175]
	v_pk_add_f32 v[104:105], v[116:117], v[172:173]
	v_lshl_add_u64 v[112:113], v[112:113], 0, v[140:141]
	v_pk_add_f32 v[110:111], v[114:115], v[170:171]
	v_pk_add_f32 v[102:103], v[102:103], v[182:183]
	v_pk_add_f32 v[100:101], v[100:101], v[180:181]
	v_pk_add_f32 v[98:99], v[98:99], v[178:179]
	global_store_dwordx4 v[112:113], v[104:107], off nt
	global_store_dwordx4 v[112:113], v[108:111], off offset:16 nt
	global_store_dwordx4 v[112:113], v[100:103], off offset:128 nt
	global_store_dwordx4 v[112:113], v[96:99], off offset:144 nt
	v_or_b32_e32 v112, 48, v144
	v_ashrrev_i32_e32 v113, 31, v112
	v_or_b32_e32 v96, 32, v144
	v_ashrrev_i32_e32 v97, 31, v96
	v_lshlrev_b64 v[152:153], 12, v[96:97]
	v_lshl_add_u64 v[108:109], v[142:143], 0, v[152:153]
	global_load_dwordx4 v[96:99], v[108:109], off offset:16
	global_load_dwordx4 v[100:103], v[108:109], off
	global_load_dwordx4 v[104:107], v[108:109], off offset:144
	s_nop 0
	global_load_dwordx4 v[108:111], v[108:109], off offset:128
	v_lshlrev_b64 v[154:155], 12, v[112:113]
	v_lshl_add_u64 v[124:125], v[142:143], 0, v[154:155]
	global_load_dwordx4 v[112:115], v[124:125], off offset:16
	global_load_dwordx4 v[116:119], v[124:125], off
	global_load_dwordx4 v[120:123], v[124:125], off offset:144
	s_nop 0
	global_load_dwordx4 v[124:127], v[124:125], off offset:128
	s_waitcnt vmcnt(0)
	v_pk_add_f32 v[88:89], v[88:89], v[96:97]
	v_lshl_add_u64 v[96:97], s[78:79], 0, v[152:153]
	v_pk_add_f32 v[94:95], v[94:95], v[102:103]
	v_pk_add_f32 v[92:93], v[92:93], v[100:101]
	v_pk_add_f32 v[76:77], v[76:77], v[108:109]
	v_lshl_add_u64 v[96:97], v[96:97], 0, v[140:141]
	v_pk_add_f32 v[90:91], v[90:91], v[98:99]
	v_pk_add_f32 v[78:79], v[78:79], v[110:111]
	v_pk_add_f32 v[74:75], v[74:75], v[106:107]
	v_pk_add_f32 v[72:73], v[72:73], v[104:105]
	global_store_dwordx4 v[96:97], v[92:95], off nt
	global_store_dwordx4 v[96:97], v[88:91], off offset:16 nt
	global_store_dwordx4 v[96:97], v[76:79], off offset:128 nt
	global_store_dwordx4 v[96:97], v[72:75], off offset:144 nt
	v_pk_add_f32 v[64:65], v[64:65], v[120:121]
	v_pk_add_f32 v[76:77], v[80:81], v[112:113]
	v_lshl_add_u64 v[80:81], s[78:79], 0, v[154:155]
	v_pk_add_f32 v[74:75], v[86:87], v[118:119]
	v_pk_add_f32 v[72:73], v[84:85], v[116:117]
	v_lshl_add_u64 v[80:81], v[80:81], 0, v[140:141]
	v_pk_add_f32 v[78:79], v[82:83], v[114:115]
	v_pk_add_f32 v[70:71], v[70:71], v[126:127]
	v_pk_add_f32 v[68:69], v[68:69], v[124:125]
	v_pk_add_f32 v[66:67], v[66:67], v[122:123]
	global_store_dwordx4 v[80:81], v[72:75], off nt
	global_store_dwordx4 v[80:81], v[76:79], off offset:16 nt
	global_store_dwordx4 v[80:81], v[68:71], off offset:128 nt
	global_store_dwordx4 v[80:81], v[64:67], off offset:144 nt
	s_nop 1
	v_add_u32_e32 v64, 0x80, v144
	v_ashrrev_i32_e32 v65, 31, v64
	v_lshlrev_b64 v[96:97], 12, v[64:65]
	v_lshl_add_u64 v[80:81], v[142:143], 0, v[96:97]
	global_load_dwordx4 v[64:67], v[80:81], off offset:16
	global_load_dwordx4 v[68:71], v[80:81], off
	global_load_dwordx4 v[72:75], v[80:81], off offset:144
	global_load_dwordx4 v[76:79], v[80:81], off offset:128
	v_add_u32_e32 v80, 0x90, v144
	v_ashrrev_i32_e32 v81, 31, v80
	v_lshlrev_b64 v[98:99], 12, v[80:81]
	v_lshl_add_u64 v[100:101], v[142:143], 0, v[98:99]
	global_load_dwordx4 v[80:83], v[100:101], off offset:16
	global_load_dwordx4 v[84:87], v[100:101], off
	global_load_dwordx4 v[88:91], v[100:101], off offset:144
	global_load_dwordx4 v[92:95], v[100:101], off offset:128
	s_waitcnt vmcnt(0)
	v_pk_add_f32 v[56:57], v[56:57], v[64:65]
	v_lshl_add_u64 v[64:65], s[78:79], 0, v[96:97]
	v_pk_add_f32 v[62:63], v[62:63], v[70:71]
	v_pk_add_f32 v[60:61], v[60:61], v[68:69]
	v_pk_add_f32 v[44:45], v[44:45], v[76:77]
	v_lshl_add_u64 v[64:65], v[64:65], 0, v[140:141]
	v_pk_add_f32 v[58:59], v[58:59], v[66:67]
	v_pk_add_f32 v[46:47], v[46:47], v[78:79]
	v_pk_add_f32 v[42:43], v[42:43], v[74:75]
	v_pk_add_f32 v[40:41], v[40:41], v[72:73]
	global_store_dwordx4 v[64:65], v[60:63], off nt
	global_store_dwordx4 v[64:65], v[56:59], off offset:16 nt
	global_store_dwordx4 v[64:65], v[44:47], off offset:128 nt
	global_store_dwordx4 v[64:65], v[40:43], off offset:144 nt
	v_pk_add_f32 v[32:33], v[32:33], v[88:89]
	v_pk_add_f32 v[44:45], v[48:49], v[80:81]
	v_lshl_add_u64 v[48:49], s[78:79], 0, v[98:99]
	v_pk_add_f32 v[42:43], v[54:55], v[86:87]
	v_pk_add_f32 v[40:41], v[52:53], v[84:85]
	v_lshl_add_u64 v[48:49], v[48:49], 0, v[140:141]
	v_pk_add_f32 v[46:47], v[50:51], v[82:83]
	v_pk_add_f32 v[38:39], v[38:39], v[94:95]
	v_pk_add_f32 v[36:37], v[36:37], v[92:93]
	v_pk_add_f32 v[34:35], v[34:35], v[90:91]
	global_store_dwordx4 v[48:49], v[40:43], off nt
	global_store_dwordx4 v[48:49], v[44:47], off offset:16 nt
	global_store_dwordx4 v[48:49], v[36:39], off offset:128 nt
	global_store_dwordx4 v[48:49], v[32:35], off offset:144 nt
	s_nop 1
	v_add_u32_e32 v32, 0xa0, v144
	v_ashrrev_i32_e32 v33, 31, v32
	v_lshlrev_b64 v[60:61], 12, v[32:33]
	v_lshl_add_u64 v[48:49], v[142:143], 0, v[60:61]
	global_load_dwordx4 v[40:43], v[48:49], off offset:16
	global_load_dwordx4 v[44:47], v[48:49], off
	global_load_dwordx4 v[32:35], v[48:49], off offset:144
	global_load_dwordx4 v[36:39], v[48:49], off offset:128
	v_add_u32_e32 v48, 0xb0, v144
	v_ashrrev_i32_e32 v49, 31, v48
	v_lshlrev_b64 v[62:63], 12, v[48:49]
	v_lshl_add_u64 v[68:69], v[142:143], 0, v[62:63]
	global_load_dwordx4 v[48:51], v[68:69], off offset:16
	global_load_dwordx4 v[56:59], v[68:69], off
	global_load_dwordx4 v[52:55], v[68:69], off offset:144
	global_load_dwordx4 v[64:67], v[68:69], off offset:128
	s_waitcnt vmcnt(0)
	v_pk_add_f32 v[26:27], v[26:27], v[42:43]
	v_pk_add_f32 v[30:31], v[30:31], v[46:47]
	v_pk_add_f32 v[12:13], v[12:13], v[32:33]
	v_lshl_add_u64 v[32:33], s[78:79], 0, v[60:61]
	v_pk_add_f32 v[28:29], v[28:29], v[44:45]
	v_lshl_add_u64 v[32:33], v[32:33], 0, v[140:141]
	v_pk_add_f32 v[24:25], v[24:25], v[40:41]
	v_pk_add_f32 v[22:23], v[22:23], v[38:39]
	v_pk_add_f32 v[20:21], v[20:21], v[36:37]
	v_pk_add_f32 v[14:15], v[14:15], v[34:35]
	global_store_dwordx4 v[32:33], v[28:31], off nt
	global_store_dwordx4 v[32:33], v[24:27], off offset:16 nt
	global_store_dwordx4 v[32:33], v[20:23], off offset:128 nt
	global_store_dwordx4 v[32:33], v[12:15], off offset:144 nt
	v_pk_add_f32 v[10:11], v[10:11], v[50:51]
	v_pk_add_f32 v[8:9], v[8:9], v[48:49]
	v_pk_add_f32 v[12:13], v[16:17], v[56:57]
	v_lshl_add_u64 v[16:17], s[78:79], 0, v[62:63]
	v_pk_add_f32 v[14:15], v[18:19], v[58:59]
	v_lshl_add_u64 v[16:17], v[16:17], 0, v[140:141]
	v_pk_add_f32 v[6:7], v[6:7], v[66:67]
	v_pk_add_f32 v[4:5], v[4:5], v[64:65]
	v_pk_add_f32 v[2:3], v[2:3], v[54:55]
	v_pk_add_f32 v[0:1], v[0:1], v[52:53]
	global_store_dwordx4 v[16:17], v[12:15], off nt
	global_store_dwordx4 v[16:17], v[8:11], off offset:16 nt
	global_store_dwordx4 v[16:17], v[4:7], off offset:128 nt
	global_store_dwordx4 v[16:17], v[0:3], off offset:144 nt
	s_cbranch_vccz .LBB0_877
	s_waitcnt vmcnt(0)
	s_cmpk_gt_u32 s16, 0xff
	s_cbranch_scc1 .LBB0_892
	s_barrier
